# g7 + P2 GELU 2/x via v_rcp_f32 + P8 epilogue conv-weight loads hoisted above LDS exchange
# baseline (speedup 1.0000x reference)
; DI f32x4 mfma16(bf16x8 a, bf16x8 b, f32x4 c) { return __builtin_amdgcn_mfma_f32_16x16x32_bf16(a, b, c, 0, 0, 0); }
; template <int NI, class XL, class EP>
; DI void gemm_tile(const u16* __restrict__ W, int ldw, int f0, int t0, int K, XL xl, EP ep, unsigned char* smem) {
;     ...
;   for (int it = 0; it < nk; ++it) {
;     const u16* Ws = S0 + (it & 1) * BUF; const u16* Xs = Ws + 128 * LST;
;     __builtin_amdgcn_s_setprio(1);
;     bf16x8 a[4];
; #pragma unroll
;     for (int mi = 0; mi < 4; ++mi) a[mi] = *(const bf16x8*)(Ws + (wf * 64 + mi * 16 + lr) * LST + lq * 8);
; #pragma unroll
;     for (int ni = 0; ni < NI; ++ni) {
;       const bf16x8 b = *(const bf16x8*)(Xs + (wt * (NI * 16) + ni * 16 + lr) * LST + lq * 8);
; #pragma unroll
;       for (int mi = 0; mi < 4; ++mi) acc[mi][ni] = mfma16(a[mi], b, acc[mi][ni]);
;     }
;     __builtin_amdgcn_sched_group_barrier(0x100, 6, 0);
; #pragma unroll
;     for (int ni = 0; ni < NI; ++ni) { __builtin_amdgcn_sched_group_barrier(0x008, 4, 0); if (ni + 2 < NI) __builtin_amdgcn_sched_group_barrier(0x100, 1, 0); }
;     __builtin_amdgcn_s_setprio(0);
;     if (it + 1 < nk) lstore((it + 1) & 1);
;     if (it + 2 < nk) gload(it + 2);
;     __syncthreads();
;   }
; DI void phase2(const Params& p, int bid, int nblk, unsigned char* smem) {
;     ...
;       const u16* W = (const u16*)(p.ws + (kv ? OFF_W1V : OFF_W1K));
;       XCmp xl{(const u16*)(p.ws + OFF_KVC), kv * 256};
;       const float* b1 = (const float*)(p.ws + OFF_B1) + kv * 256;
;       u16* hid = (u16*)(p.ws + OFF_HID) + (size_t)kv * CROWS * 256;
;       gemm_tile<4>(W, 256, tn * 128, tm * 128, 2048, xl, [&](f32x4 (&acc)[4][4], int fb, int tb, int lr, int lq, int wf, int wt) {
.LBB0_356:
	s_bitcmp1_b32 s21, 0
	s_cselect_b32 s54, 0, 0x6000
	s_setprio 1
	v_or_b32_e32 v98, s54, v92
	v_lshl_add_u32 v110, v93, 1, v98
	ds_read_b128 v[94:97], v110
	v_lshl_add_u32 v118, v91, 1, v98
	ds_read_b128 v[98:101], v110 offset:1536
	ds_read_b128 v[106:109], v110 offset:3072
	ds_read_b128 v[110:113], v110 offset:4608
	ds_read_b128 v[102:105], v118 offset:12288
	ds_read_b128 v[114:117], v118 offset:13824
	s_waitcnt lgkmcnt(1)
	v_mfma_f32_16x16x32_bf16 v[76:79], v[94:97], v[102:105], v[76:79]
	v_mfma_f32_16x16x32_bf16 v[68:71], v[98:101], v[102:105], v[68:71]
	v_mfma_f32_16x16x32_bf16 v[52:55], v[106:109], v[102:105], v[52:55]
	v_mfma_f32_16x16x32_bf16 v[36:39], v[110:113], v[102:105], v[36:39]
	ds_read_b128 v[102:105], v118 offset:15360
	s_waitcnt lgkmcnt(1)
	v_mfma_f32_16x16x32_bf16 v[72:75], v[94:97], v[114:117], v[72:75]
	v_mfma_f32_16x16x32_bf16 v[60:63], v[98:101], v[114:117], v[60:63]
	v_mfma_f32_16x16x32_bf16 v[44:47], v[106:109], v[114:117], v[44:47]
	v_mfma_f32_16x16x32_bf16 v[28:31], v[110:113], v[114:117], v[28:31]
	ds_read_b128 v[114:117], v118 offset:16896
	s_waitcnt lgkmcnt(1)
	v_mfma_f32_16x16x32_bf16 v[64:67], v[94:97], v[102:105], v[64:67]
	v_mfma_f32_16x16x32_bf16 v[48:51], v[98:101], v[102:105], v[48:51]
	v_mfma_f32_16x16x32_bf16 v[32:35], v[106:109], v[102:105], v[32:35]
	v_mfma_f32_16x16x32_bf16 v[20:23], v[110:113], v[102:105], v[20:23]
	s_waitcnt lgkmcnt(0)
	v_mfma_f32_16x16x32_bf16 v[56:59], v[94:97], v[114:117], v[56:59]
	v_mfma_f32_16x16x32_bf16 v[40:43], v[98:101], v[114:117], v[40:43]
	v_mfma_f32_16x16x32_bf16 v[24:27], v[106:109], v[114:117], v[24:27]
	v_mfma_f32_16x16x32_bf16 v[16:19], v[110:113], v[114:117], v[16:19]
	s_setprio 0
	s_cselect_b32 s54, 0x6000, 0
	s_and_b32 s55, s33, 0xfc00
	s_and_b32 s56, s53, 32
	v_add_u32_e32 v94, s54, v90
	s_add_u32 s54, s4, s55
	s_addc_u32 s55, s5, 0
	s_lshl_b32 s56, s56, 1
	s_add_u32 s54, s54, s56
	s_addc_u32 s55, s55, 0
	s_waitcnt vmcnt(0)
	ds_write_b128 v94, v[8:11] offset:12384
	v_lshl_add_u64 v[8:9], s[54:55], 0, v[80:81]
	ds_write_b128 v94, v[4:7]
	ds_write_b128 v94, v[0:3] offset:96
	ds_write_b128 v94, v[12:15] offset:12288
	global_load_dwordx4 v[4:7], v[82:83], off
	global_load_dwordx4 v[0:3], v[82:83], off offset:64
	global_load_dwordx4 v[12:15], v[8:9], off
	s_addk_i32 s33, 0x200
	global_load_dwordx4 v[8:11], v[8:9], off offset:128
	s_add_i32 s53, s53, 32
	s_add_i32 s21, s21, 1
	v_lshl_add_u64 v[82:83], v[82:83], 0, s[18:19]
	s_cmp_lg_u32 s21, 63
	s_waitcnt lgkmcnt(0)
	s_barrier
	s_cbranch_scc1 .LBB0_356
	s_lshl_b64 s[0:1], s[0:1], 2
	s_add_u32 s0, s26, s0
	s_addc_u32 s1, s27, s1
	s_mul_hi_i32 s4, s20, 0x7f0000
	s_mul_i32 s20, s20, 0x7f0000
	s_setprio 1
	v_lshl_add_u32 v80, v93, 1, v92
	ds_read_b128 v[94:97], v80
	ds_read_b128 v[98:101], v80 offset:1536
	ds_read_b128 v[106:109], v80 offset:3072
	ds_read_b128 v[110:113], v80 offset:4608
	v_lshl_add_u32 v82, v91, 1, v92
	ds_read_b128 v[102:105], v82 offset:12288
	ds_read_b128 v[114:117], v82 offset:13824
	s_waitcnt lgkmcnt(1)
	v_mfma_f32_16x16x32_bf16 v[76:79], v[94:97], v[102:105], v[76:79]
	v_mfma_f32_16x16x32_bf16 v[68:71], v[98:101], v[102:105], v[68:71]
	v_mfma_f32_16x16x32_bf16 v[52:55], v[106:109], v[102:105], v[52:55]
	v_mfma_f32_16x16x32_bf16 v[36:39], v[110:113], v[102:105], v[36:39]
	ds_read_b128 v[102:105], v82 offset:15360
	s_waitcnt lgkmcnt(1)
	v_mfma_f32_16x16x32_bf16 v[72:75], v[94:97], v[114:117], v[72:75]
	v_mfma_f32_16x16x32_bf16 v[118:121], v[98:101], v[114:117], v[60:63]
	v_mfma_f32_16x16x32_bf16 v[122:125], v[106:109], v[114:117], v[44:47]
	v_mfma_f32_16x16x32_bf16 v[114:117], v[110:113], v[114:117], v[28:31]
	s_nop 2
	ds_read_b128 v[28:31], v82 offset:16896
	s_waitcnt lgkmcnt(1)
	v_mfma_f32_16x16x32_bf16 v[64:67], v[94:97], v[102:105], v[64:67]
	v_mfma_f32_16x16x32_bf16 v[48:51], v[98:101], v[102:105], v[48:51]
	v_mfma_f32_16x16x32_bf16 v[32:35], v[106:109], v[102:105], v[32:35]
	v_mfma_f32_16x16x32_bf16 v[102:105], v[110:113], v[102:105], v[20:23]
	s_waitcnt lgkmcnt(0)
	v_mfma_f32_16x16x32_bf16 v[92:95], v[94:97], v[28:31], v[56:59]
	v_mfma_f32_16x16x32_bf16 v[96:99], v[98:101], v[28:31], v[40:43]
	v_mfma_f32_16x16x32_bf16 v[106:109], v[106:109], v[28:31], v[24:27]
	v_mfma_f32_16x16x32_bf16 v[110:113], v[110:113], v[28:31], v[16:19]
	s_setprio 0
	s_add_u32 s20, s28, s20
	s_waitcnt vmcnt(3)
	ds_write_b128 v90, v[4:7] offset:24576
	s_waitcnt vmcnt(2)
	ds_write_b128 v90, v[0:3] offset:24672
	s_waitcnt vmcnt(1)
	ds_write_b128 v90, v[12:15] offset:36864
	s_waitcnt vmcnt(0)
	ds_write_b128 v90, v[8:11] offset:36960
	s_waitcnt lgkmcnt(0)
	s_barrier
	s_addc_u32 s21, s29, s4
	s_setprio 1
	ds_read_b128 v[0:3], v80 offset:24576
	ds_read_b128 v[16:19], v80 offset:26112
	ds_read_b128 v[126:129], v80 offset:27648
	ds_read_b128 v[130:133], v80 offset:29184
	ds_read_b128 v[4:7], v82 offset:36864
	ds_read_b128 v[8:11], v82 offset:38400
	s_waitcnt lgkmcnt(1)
	v_mfma_f32_16x16x32_bf16 v[76:79], v[0:3], v[4:7], v[76:79]
	v_mfma_f32_16x16x32_bf16 v[44:47], v[16:19], v[4:7], v[68:71]
	v_mfma_f32_16x16x32_bf16 v[28:31], v[126:129], v[4:7], v[52:55]
	v_mfma_f32_16x16x32_bf16 v[12:15], v[130:133], v[4:7], v[36:39]
	ds_read_b128 v[4:7], v82 offset:39936
	s_waitcnt lgkmcnt(1)
	v_mfma_f32_16x16x32_bf16 v[60:63], v[0:3], v[8:11], v[72:75]
	v_mfma_f32_16x16x32_bf16 v[40:43], v[16:19], v[8:11], v[118:121]
	v_mfma_f32_16x16x32_bf16 v[24:27], v[126:129], v[8:11], v[122:125]
	v_mfma_f32_16x16x32_bf16 v[8:11], v[130:133], v[8:11], v[114:117]
	ds_read_b128 v[52:55], v82 offset:41472
	s_waitcnt lgkmcnt(1)
	v_mfma_f32_16x16x32_bf16 v[56:59], v[0:3], v[4:7], v[64:67]
	v_mfma_f32_16x16x32_bf16 v[36:39], v[16:19], v[4:7], v[48:51]
	v_mfma_f32_16x16x32_bf16 v[20:23], v[126:129], v[4:7], v[32:35]
	v_mfma_f32_16x16x32_bf16 v[4:7], v[130:133], v[4:7], v[102:105]
	s_waitcnt lgkmcnt(0)
	v_mfma_f32_16x16x32_bf16 v[48:51], v[0:3], v[52:55], v[92:95]
	v_mfma_f32_16x16x32_bf16 v[32:35], v[16:19], v[52:55], v[96:99]
	v_mfma_f32_16x16x32_bf16 v[16:19], v[126:129], v[52:55], v[106:109]
	v_mfma_f32_16x16x32_bf16 v[0:3], v[130:133], v[52:55], v[110:113]
	s_setprio 0
	v_add_u32_e32 v72, s7, v89
	v_lshl_or_b32 v66, v86, 2, v72
	v_ashrrev_i32_e32 v67, 31, v66
	v_lshl_add_u64 v[68:69], v[66:67], 2, s[0:1]
	s_barrier
; DI void store4(u16* dst, f32x4 v) { uint2 w; w.x = cvtpk(v[0], v[1]); w.y = cvtpk(v[2], v[3]); *(uint2*)dst = w; }
; DI void phase2(const Params& p, int bid, int nblk, unsigned char* smem) {
;     ...
;         for (int mi = 0; mi < 4; ++mi) {
;           const int f = fb + mi * 16 + lq * 4; const float4 bb = *(const float4*)(b1 + f);
; #pragma unroll
;           for (int ni = 0; ni < 4; ++ni) {
;             const int t = tb + ni * 16 + lr; f32x4 v = acc[mi][ni]; v[0] += bb.x; v[1] += bb.y; v[2] += bb.z; v[3] += bb.w;
; #pragma unroll
;             for (int j = 0; j < 4; ++j) { const float xx = v[j]; const float u = 0.7978845608028654f * (xx + 0.044715f * xx * xx * xx); const float th = 1.0f - 2.0f / (__expf(2.0f * u) + 1.0f); v[j] = 0.5f * xx * (1.0f + th); }
;             store4(hid + ((size_t)(f >> 5) * CROWS + t) * 32 + (f & 31), v);
;           }
	global_load_dwordx4 v[52:55], v[68:69], off
	v_and_b32_e32 v64, 64, v87
	v_or3_b32 v64, v64, s6, v88
	v_ashrrev_i32_e32 v67, 5, v72
	v_ashrrev_i32_e32 v65, 31, v64
	v_mad_i64_i32 v[70:71], s[0:1], v67, s52, v[64:65]
	v_lshlrev_b64 v[70:71], 6, v[70:71]
	v_lshl_add_u64 v[70:71], s[20:21], 0, v[70:71]
	s_waitcnt vmcnt(0)
	v_pk_add_f32 v[74:75], v[76:77], v[52:53]
	v_pk_add_f32 v[76:77], v[78:79], v[54:55]
	v_mul_f32_e32 v73, 0x3d372713, v74
	v_mul_f32_e32 v80, 0x3d372713, v75
	v_mul_f32_e32 v87, 0x3d372713, v76
	v_mul_f32_e32 v73, v74, v73
	v_mul_f32_e32 v80, v75, v80
	v_pk_mul_f32 v[78:79], v[74:75], 0.5 op_sel_hi:[1,0]
	v_mul_f32_e32 v87, v76, v87
	v_fma_f32 v73, v74, v73, v74
	v_fma_f32 v74, v75, v80, v75
	v_mul_f32_e32 v88, 0x3d372713, v77
	v_fma_f32 v75, v76, v87, v76
	v_mul_f32_e32 v73, 0x3f4c422a, v73
	v_mul_f32_e32 v74, 0x3f4c422a, v74
	v_mul_f32_e32 v88, v77, v88
	v_mul_f32_e32 v75, 0x3f4c422a, v75
	v_add_f32_e32 v73, v73, v73
	v_add_f32_e32 v74, v74, v74
	v_pk_mul_f32 v[82:83], v[76:77], 0.5 op_sel_hi:[1,0]
	v_fma_f32 v76, v77, v88, v77
	v_add_f32_e32 v75, v75, v75
	v_mul_f32_e32 v73, 0x3fb8aa3b, v73
	v_mul_f32_e32 v77, 0x3fb8aa3b, v74
	v_mul_f32_e32 v80, 0x3fb8aa3b, v75
	v_exp_f32_e32 v74, v73
	v_exp_f32_e32 v75, v77
	v_mul_f32_e32 v76, 0x3f4c422a, v76
	v_add_f32_e32 v76, v76, v76
	v_mul_f32_e32 v87, 0x3fb8aa3b, v76
	v_pk_add_f32 v[74:75], v[74:75], 1.0 op_sel_hi:[1,0]
	v_exp_f32_e32 v76, v80
	v_pk_add_f32 v[60:61], v[60:61], v[52:53]
	v_exp_f32_e32 v77, v87
	v_mul_f32_e32 v89, 0x3d372713, v60
	v_mul_f32_e32 v73, v60, v89
	s_mov_b64 vcc, s[0:1]
	v_fma_f32 v73, v60, v73, v60
	v_rcp_f32_e32 v75, v75
	s_nop 0
	v_add_f32_e32 v75, v75, v75
	v_pk_add_f32 v[76:77], v[76:77], 1.0 op_sel_hi:[1,0]
	v_rcp_f32_e32 v74, v74
	s_nop 0
	v_add_f32_e32 v74, v74, v74
	v_mul_f32_e32 v73, 0x3f4c422a, v73
	v_pk_add_f32 v[74:75], v[74:75], 1.0 op_sel_hi:[1,0] neg_lo:[1,0] neg_hi:[1,0]
	v_add_f32_e32 v73, v73, v73
	v_pk_add_f32 v[74:75], v[74:75], 1.0 op_sel_hi:[1,0]
	v_mul_f32_e32 v73, 0x3fb8aa3b, v73
	v_pk_mul_f32 v[74:75], v[78:79], v[74:75]
	v_exp_f32_e32 v78, v73
	v_mul_f32_e32 v73, 0x3d372713, v61
	v_mul_f32_e32 v73, v61, v73
	v_fma_f32 v73, v61, v73, v61
	v_mul_f32_e32 v73, 0x3f4c422a, v73
	v_add_f32_e32 v73, v73, v73
	v_mul_f32_e32 v73, 0x3fb8aa3b, v73
	v_exp_f32_e32 v79, v73
	s_mov_b64 vcc, s[4:5]
	s_mov_b64 vcc, s[6:7]
	v_rcp_f32_e32 v77, v77
	s_nop 0
	v_add_f32_e32 v77, v77, v77
	v_pk_add_f32 v[78:79], v[78:79], 1.0 op_sel_hi:[1,0]
	v_rcp_f32_e32 v76, v76
	s_nop 0
	v_add_f32_e32 v76, v76, v76
	v_pk_add_f32 v[76:77], v[76:77], 1.0 op_sel_hi:[1,0] neg_lo:[1,0] neg_hi:[1,0]
	v_lshlrev_b32_e32 v80, 3, v86
	v_pk_add_f32 v[76:77], v[76:77], 1.0 op_sel_hi:[1,0]
	v_cvt_pk_bf16_f32 v74, v74, v75
	v_pk_mul_f32 v[76:77], v[82:83], v[76:77]
	v_lshl_add_u64 v[82:83], v[70:71], 0, v[80:81]
	v_cvt_pk_bf16_f32 v75, v76, v77
	global_store_dwordx2 v[82:83], v[74:75], off
	v_rcp_f32_e32 v75, v79
	s_nop 0
	v_add_f32_e32 v75, v75, v75
	v_pk_add_f32 v[62:63], v[62:63], v[54:55]
	v_mul_f32_e32 v74, 0x3d372713, v62
	v_mul_f32_e32 v74, v62, v74
	v_fma_f32 v74, v62, v74, v62
	v_mul_f32_e32 v74, 0x3f4c422a, v74
	v_add_f32_e32 v74, v74, v74
	v_mul_f32_e32 v74, 0x3fb8aa3b, v74
	v_exp_f32_e32 v76, v74
	v_mul_f32_e32 v74, 0x3d372713, v63
	v_mul_f32_e32 v74, v63, v74
	v_fma_f32 v74, v63, v74, v63
	v_mul_f32_e32 v74, 0x3f4c422a, v74
	v_add_f32_e32 v74, v74, v74
	v_mul_f32_e32 v74, 0x3fb8aa3b, v74
	v_exp_f32_e32 v77, v74
	v_rcp_f32_e32 v74, v78
	s_nop 0
	v_add_f32_e32 v74, v74, v74
	v_pk_add_f32 v[74:75], v[74:75], 1.0 op_sel_hi:[1,0] neg_lo:[1,0] neg_hi:[1,0]
	v_pk_add_f32 v[76:77], v[76:77], 1.0 op_sel_hi:[1,0]
	v_pk_mul_f32 v[60:61], v[60:61], 0.5 op_sel_hi:[1,0]
	v_pk_add_f32 v[74:75], v[74:75], 1.0 op_sel_hi:[1,0]
	v_pk_add_f32 v[56:57], v[56:57], v[52:53]
	v_pk_mul_f32 v[74:75], v[60:61], v[74:75]
	v_rcp_f32_e32 v61, v77
	s_nop 0
	v_add_f32_e32 v61, v61, v61
	v_pk_mul_f32 v[62:63], v[62:63], 0.5 op_sel_hi:[1,0]
	v_mul_f32_e32 v73, 0x3d372713, v56
	v_mul_f32_e32 v73, v56, v73
	v_fma_f32 v73, v56, v73, v56
	v_mul_f32_e32 v73, 0x3f4c422a, v73
	v_add_f32_e32 v73, v73, v73
	v_mul_f32_e32 v73, 0x3fb8aa3b, v73
	v_exp_f32_e32 v78, v73
	v_mul_f32_e32 v73, 0x3d372713, v57
	v_mul_f32_e32 v73, v57, v73
	v_fma_f32 v73, v57, v73, v57
	v_mul_f32_e32 v73, 0x3f4c422a, v73
	v_add_f32_e32 v73, v73, v73
	v_mul_f32_e32 v73, 0x3fb8aa3b, v73
	v_exp_f32_e32 v79, v73
	v_rcp_f32_e32 v60, v76
	s_nop 0
	v_add_f32_e32 v60, v60, v60
	v_pk_add_f32 v[60:61], v[60:61], 1.0 op_sel_hi:[1,0] neg_lo:[1,0] neg_hi:[1,0]
	v_cvt_pk_bf16_f32 v74, v74, v75
	v_pk_add_f32 v[60:61], v[60:61], 1.0 op_sel_hi:[1,0]
	v_pk_add_f32 v[78:79], v[78:79], 1.0 op_sel_hi:[1,0]
	v_pk_mul_f32 v[76:77], v[62:63], v[60:61]
	v_or_b32_e32 v60, 16, v64
	v_ashrrev_i32_e32 v61, 31, v60
	v_mad_i64_i32 v[62:63], s[0:1], v67, s52, v[60:61]
	v_lshlrev_b64 v[62:63], 6, v[62:63]
	v_lshl_add_u64 v[62:63], s[20:21], 0, v[62:63]
	v_lshl_add_u64 v[82:83], v[62:63], 0, v[80:81]
	v_cvt_pk_bf16_f32 v75, v76, v77
	global_store_dwordx2 v[82:83], v[74:75], off
	v_rcp_f32_e32 v75, v79
	s_nop 0
	v_add_f32_e32 v75, v75, v75
	v_pk_add_f32 v[58:59], v[58:59], v[54:55]
	v_mul_f32_e32 v74, 0x3d372713, v58
	v_mul_f32_e32 v74, v58, v74
	v_fma_f32 v74, v58, v74, v58
	v_mul_f32_e32 v74, 0x3f4c422a, v74
	v_add_f32_e32 v74, v74, v74
	v_mul_f32_e32 v74, 0x3fb8aa3b, v74
	v_exp_f32_e32 v76, v74
	v_mul_f32_e32 v74, 0x3d372713, v59
	v_mul_f32_e32 v74, v59, v74
	v_fma_f32 v74, v59, v74, v59
	v_mul_f32_e32 v74, 0x3f4c422a, v74
	v_add_f32_e32 v74, v74, v74
	v_mul_f32_e32 v74, 0x3fb8aa3b, v74
	v_exp_f32_e32 v77, v74
	v_rcp_f32_e32 v74, v78
	s_nop 0
	v_add_f32_e32 v74, v74, v74
; DI void store4(u16* dst, f32x4 v) { uint2 w; w.x = cvtpk(v[0], v[1]); w.y = cvtpk(v[2], v[3]); *(uint2*)dst = w; }
; DI void phase2(const Params& p, int bid, int nblk, unsigned char* smem) {
;     ...
;         for (int mi = 0; mi < 4; ++mi) {
;           const int f = fb + mi * 16 + lq * 4; const float4 bb = *(const float4*)(b1 + f);
; #pragma unroll
;           for (int ni = 0; ni < 4; ++ni) {
;             const int t = tb + ni * 16 + lr; f32x4 v = acc[mi][ni]; v[0] += bb.x; v[1] += bb.y; v[2] += bb.z; v[3] += bb.w;
; #pragma unroll
;             for (int j = 0; j < 4; ++j) { const float xx = v[j]; const float u = 0.7978845608028654f * (xx + 0.044715f * xx * xx * xx); const float th = 1.0f - 2.0f / (__expf(2.0f * u) + 1.0f); v[j] = 0.5f * xx * (1.0f + th); }
;             store4(hid + ((size_t)(f >> 5) * CROWS + t) * 32 + (f & 31), v);
;           }
	v_pk_add_f32 v[74:75], v[74:75], 1.0 op_sel_hi:[1,0] neg_lo:[1,0] neg_hi:[1,0]
	v_pk_add_f32 v[76:77], v[76:77], 1.0 op_sel_hi:[1,0]
	v_pk_mul_f32 v[56:57], v[56:57], 0.5 op_sel_hi:[1,0]
	v_pk_add_f32 v[74:75], v[74:75], 1.0 op_sel_hi:[1,0]
	v_pk_add_f32 v[48:49], v[48:49], v[52:53]
	v_pk_mul_f32 v[74:75], v[56:57], v[74:75]
	v_rcp_f32_e32 v57, v77
	s_nop 0
	v_add_f32_e32 v57, v57, v57
	v_mul_f32_e32 v52, 0x3d372713, v48
	v_mul_f32_e32 v53, 0x3d372713, v49
	v_mul_f32_e32 v52, v48, v52
	v_mul_f32_e32 v53, v49, v53
	v_fma_f32 v52, v48, v52, v48
	v_fma_f32 v53, v49, v53, v49
	v_mul_f32_e32 v52, 0x3f4c422a, v52
	v_mul_f32_e32 v53, 0x3f4c422a, v53
	v_add_f32_e32 v52, v52, v52
	v_add_f32_e32 v53, v53, v53
	v_mul_f32_e32 v52, 0x3fb8aa3b, v52
	v_mul_f32_e32 v53, 0x3fb8aa3b, v53
	v_exp_f32_e32 v52, v52
	v_exp_f32_e32 v53, v53
	v_rcp_f32_e32 v56, v76
	s_nop 0
	v_add_f32_e32 v56, v56, v56
	v_pk_add_f32 v[56:57], v[56:57], 1.0 op_sel_hi:[1,0] neg_lo:[1,0] neg_hi:[1,0]
	v_pk_mul_f32 v[58:59], v[58:59], 0.5 op_sel_hi:[1,0]
	v_pk_add_f32 v[56:57], v[56:57], 1.0 op_sel_hi:[1,0]
	v_pk_add_f32 v[52:53], v[52:53], 1.0 op_sel_hi:[1,0]
	v_pk_mul_f32 v[76:77], v[58:59], v[56:57]
	v_or_b32_e32 v56, 32, v64
	v_ashrrev_i32_e32 v57, 31, v56
	v_mad_i64_i32 v[58:59], s[0:1], v67, s52, v[56:57]
	v_lshlrev_b64 v[58:59], 6, v[58:59]
	v_lshl_add_u64 v[58:59], s[20:21], 0, v[58:59]
	v_lshl_add_u64 v[78:79], v[58:59], 0, v[80:81]
	v_cvt_pk_bf16_f32 v74, v74, v75
	v_cvt_pk_bf16_f32 v75, v76, v77
	global_store_dwordx2 v[78:79], v[74:75], off
	v_pk_add_f32 v[50:51], v[50:51], v[54:55]
	v_mul_f32_e32 v54, 0x3d372713, v50
	v_mul_f32_e32 v55, 0x3d372713, v51
	v_mul_f32_e32 v54, v50, v54
	v_mul_f32_e32 v55, v51, v55
	v_fma_f32 v54, v50, v54, v50
	v_fma_f32 v55, v51, v55, v51
	v_mul_f32_e32 v54, 0x3f4c422a, v54
	v_mul_f32_e32 v55, 0x3f4c422a, v55
	v_rcp_f32_e32 v53, v53
	s_nop 0
	v_add_f32_e32 v53, v53, v53
	v_add_f32_e32 v54, v54, v54
	v_add_f32_e32 v55, v55, v55
	v_mul_f32_e32 v54, 0x3fb8aa3b, v54
	v_mul_f32_e32 v55, 0x3fb8aa3b, v55
	v_exp_f32_e32 v54, v54
	v_exp_f32_e32 v55, v55
	s_nop 0
	v_pk_add_f32 v[54:55], v[54:55], 1.0 op_sel_hi:[1,0]
	v_rcp_f32_e32 v52, v52
	s_nop 0
	v_add_f32_e32 v52, v52, v52
	v_pk_add_f32 v[52:53], v[52:53], 1.0 op_sel_hi:[1,0] neg_lo:[1,0] neg_hi:[1,0]
	v_pk_mul_f32 v[48:49], v[48:49], 0.5 op_sel_hi:[1,0]
	v_pk_add_f32 v[52:53], v[52:53], 1.0 op_sel_hi:[1,0]
	v_pk_mul_f32 v[50:51], v[50:51], 0.5 op_sel_hi:[1,0]
	v_pk_mul_f32 v[48:49], v[48:49], v[52:53]
	v_rcp_f32_e32 v53, v55
	s_nop 0
	v_add_f32_e32 v53, v53, v53
	v_cvt_pk_bf16_f32 v48, v48, v49
	v_rcp_f32_e32 v52, v54
	s_nop 0
	v_add_f32_e32 v52, v52, v52
	v_pk_add_f32 v[52:53], v[52:53], 1.0 op_sel_hi:[1,0] neg_lo:[1,0] neg_hi:[1,0]
	v_bitop3_b32 v78, v66, 28, 16 bitop3:0xc8
	v_pk_add_f32 v[52:53], v[52:53], 1.0 op_sel_hi:[1,0]
	s_nop 0
	v_pk_mul_f32 v[50:51], v[50:51], v[52:53]
	v_or_b32_e32 v52, 48, v64
	v_ashrrev_i32_e32 v53, 31, v52
	v_mad_i64_i32 v[54:55], s[0:1], v67, s52, v[52:53]
	v_lshlrev_b64 v[54:55], 6, v[54:55]
	v_lshl_add_u64 v[54:55], s[20:21], 0, v[54:55]
	v_lshl_add_u64 v[74:75], v[54:55], 0, v[80:81]
	v_cvt_pk_bf16_f32 v49, v50, v51
	global_store_dwordx2 v[74:75], v[48:49], off
	global_load_dwordx4 v[48:51], v[68:69], off offset:64
	s_waitcnt vmcnt(0)
	v_pk_add_f32 v[44:45], v[44:45], v[48:49]
	s_nop 0
	v_mul_f32_e32 v67, 0x3d372713, v44
	v_mul_f32_e32 v67, v44, v67
	v_fma_f32 v67, v44, v67, v44
	v_mul_f32_e32 v67, 0x3f4c422a, v67
	v_add_f32_e32 v67, v67, v67
	v_mul_f32_e32 v67, 0x3fb8aa3b, v67
	v_exp_f32_e32 v74, v67
	v_mul_f32_e32 v67, 0x3d372713, v45
	v_mul_f32_e32 v67, v45, v67
	v_fma_f32 v67, v45, v67, v45
	v_mul_f32_e32 v67, 0x3f4c422a, v67
	v_add_f32_e32 v67, v67, v67
	v_mul_f32_e32 v67, 0x3fb8aa3b, v67
	v_exp_f32_e32 v75, v67
	v_pk_add_f32 v[46:47], v[46:47], v[50:51]
	v_pk_mul_f32 v[44:45], v[44:45], 0.5 op_sel_hi:[1,0]
	v_pk_add_f32 v[42:43], v[42:43], v[50:51]
	v_pk_add_f32 v[74:75], v[74:75], 1.0 op_sel_hi:[1,0]
	v_pk_add_f32 v[36:37], v[36:37], v[48:49]
	v_pk_add_f32 v[38:39], v[38:39], v[50:51]
	v_pk_add_f32 v[32:33], v[32:33], v[48:49]
	v_pk_add_f32 v[34:35], v[34:35], v[50:51]
	v_rcp_f32_e32 v75, v75
	s_nop 0
	v_add_f32_e32 v75, v75, v75
	v_mul_f32_e32 v76, 0x3d372713, v46
	v_mul_f32_e32 v77, 0x3d372713, v47
	v_mul_f32_e32 v76, v46, v76
	v_mul_f32_e32 v77, v47, v77
	v_fma_f32 v76, v46, v76, v46
	v_fma_f32 v77, v47, v77, v47
	v_mul_f32_e32 v76, 0x3f4c422a, v76
	v_mul_f32_e32 v77, 0x3f4c422a, v77
	v_add_f32_e32 v76, v76, v76
	v_add_f32_e32 v77, v77, v77
	v_mul_f32_e32 v76, 0x3fb8aa3b, v76
	v_mul_f32_e32 v77, 0x3fb8aa3b, v77
	v_exp_f32_e32 v76, v76
	v_exp_f32_e32 v77, v77
	v_rcp_f32_e32 v74, v74
	s_nop 0
	v_add_f32_e32 v74, v74, v74
	v_pk_add_f32 v[74:75], v[74:75], 1.0 op_sel_hi:[1,0] neg_lo:[1,0] neg_hi:[1,0]
	v_pk_add_f32 v[76:77], v[76:77], 1.0 op_sel_hi:[1,0]
	v_pk_add_f32 v[74:75], v[74:75], 1.0 op_sel_hi:[1,0]
	v_pk_mul_f32 v[44:45], v[44:45], v[74:75]
	v_pk_mul_f32 v[46:47], v[46:47], 0.5 op_sel_hi:[1,0]
	v_cvt_pk_bf16_f32 v44, v44, v45
	v_rcp_f32_e32 v75, v77
	s_nop 0
	v_add_f32_e32 v75, v75, v75
	v_rcp_f32_e32 v74, v76
	s_nop 0
	v_add_f32_e32 v74, v74, v74
	v_pk_add_f32 v[74:75], v[74:75], 1.0 op_sel_hi:[1,0] neg_lo:[1,0] neg_hi:[1,0]
	s_nop 0
	v_pk_add_f32 v[74:75], v[74:75], 1.0 op_sel_hi:[1,0]
	s_nop 0
	v_pk_mul_f32 v[46:47], v[46:47], v[74:75]
	v_pk_add_f32 v[74:75], v[40:41], v[48:49]
	v_mov_b32_e32 v41, v81
	v_mul_f32_e32 v40, 0x3d372713, v74
	v_mul_f32_e32 v40, v74, v40
	v_fma_f32 v40, v74, v40, v74
	v_mul_f32_e32 v40, 0x3f4c422a, v40
	v_add_f32_e32 v40, v40, v40
	v_mul_f32_e32 v40, 0x3fb8aa3b, v40
	v_exp_f32_e32 v76, v40
	v_mul_f32_e32 v40, 0x3d372713, v75
; DI void store4(u16* dst, f32x4 v) { uint2 w; w.x = cvtpk(v[0], v[1]); w.y = cvtpk(v[2], v[3]); *(uint2*)dst = w; }
; DI void phase2(const Params& p, int bid, int nblk, unsigned char* smem) {
;     ...
;         for (int mi = 0; mi < 4; ++mi) {
;           const int f = fb + mi * 16 + lq * 4; const float4 bb = *(const float4*)(b1 + f);
; #pragma unroll
;           for (int ni = 0; ni < 4; ++ni) {
;             const int t = tb + ni * 16 + lr; f32x4 v = acc[mi][ni]; v[0] += bb.x; v[1] += bb.y; v[2] += bb.z; v[3] += bb.w;
; #pragma unroll
;             for (int j = 0; j < 4; ++j) { const float xx = v[j]; const float u = 0.7978845608028654f * (xx + 0.044715f * xx * xx * xx); const float th = 1.0f - 2.0f / (__expf(2.0f * u) + 1.0f); v[j] = 0.5f * xx * (1.0f + th); }
;             store4(hid + ((size_t)(f >> 5) * CROWS + t) * 32 + (f & 31), v);
;           }
	v_mul_f32_e32 v40, v75, v40
	v_fma_f32 v40, v75, v40, v75
	v_mul_f32_e32 v40, 0x3f4c422a, v40
	v_add_f32_e32 v40, v40, v40
	v_mul_f32_e32 v40, 0x3fb8aa3b, v40
	v_exp_f32_e32 v77, v40
	v_lshlrev_b32_e32 v40, 1, v78
	v_lshl_add_u64 v[70:71], v[70:71], 0, v[40:41]
	v_cvt_pk_bf16_f32 v45, v46, v47
	v_pk_add_f32 v[76:77], v[76:77], 1.0 op_sel_hi:[1,0]
	global_store_dwordx2 v[70:71], v[44:45], off
	s_nop 0
	v_rcp_f32_e32 v45, v77
	s_nop 0
	v_add_f32_e32 v45, v45, v45
	v_mul_f32_e32 v46, 0x3d372713, v42
	v_mul_f32_e32 v47, 0x3d372713, v43
	v_mul_f32_e32 v46, v42, v46
	v_mul_f32_e32 v47, v43, v47
	v_fma_f32 v46, v42, v46, v42
	v_fma_f32 v47, v43, v47, v43
	v_mul_f32_e32 v46, 0x3f4c422a, v46
	v_mul_f32_e32 v47, 0x3f4c422a, v47
	v_add_f32_e32 v46, v46, v46
	v_add_f32_e32 v47, v47, v47
	v_mul_f32_e32 v46, 0x3fb8aa3b, v46
	v_mul_f32_e32 v47, 0x3fb8aa3b, v47
	v_exp_f32_e32 v46, v46
	v_exp_f32_e32 v47, v47
	v_rcp_f32_e32 v44, v76
	s_nop 0
	v_add_f32_e32 v44, v44, v44
	v_pk_add_f32 v[44:45], v[44:45], 1.0 op_sel_hi:[1,0] neg_lo:[1,0] neg_hi:[1,0]
	v_pk_add_f32 v[46:47], v[46:47], 1.0 op_sel_hi:[1,0]
	v_pk_mul_f32 v[70:71], v[74:75], 0.5 op_sel_hi:[1,0]
	v_pk_add_f32 v[44:45], v[44:45], 1.0 op_sel_hi:[1,0]
	v_pk_mul_f32 v[42:43], v[42:43], 0.5 op_sel_hi:[1,0]
	v_pk_mul_f32 v[44:45], v[70:71], v[44:45]
	v_rcp_f32_e32 v47, v47
	s_nop 0
	v_add_f32_e32 v47, v47, v47
	v_cvt_pk_bf16_f32 v44, v44, v45
	v_rcp_f32_e32 v46, v46
	s_nop 0
	v_add_f32_e32 v46, v46, v46
	v_mul_f32_e32 v67, 0x3d372713, v36
	v_mul_f32_e32 v67, v36, v67
	v_fma_f32 v67, v36, v67, v36
	v_mul_f32_e32 v67, 0x3f4c422a, v67
	v_add_f32_e32 v67, v67, v67
	v_mul_f32_e32 v67, 0x3fb8aa3b, v67
	v_exp_f32_e32 v70, v67
	v_mul_f32_e32 v67, 0x3d372713, v37
	v_mul_f32_e32 v67, v37, v67
	v_fma_f32 v67, v37, v67, v37
	v_mul_f32_e32 v67, 0x3f4c422a, v67
	v_add_f32_e32 v67, v67, v67
	v_mul_f32_e32 v67, 0x3fb8aa3b, v67
	v_exp_f32_e32 v71, v67
	v_pk_add_f32 v[46:47], v[46:47], 1.0 op_sel_hi:[1,0] neg_lo:[1,0] neg_hi:[1,0]
	v_pk_mul_f32 v[36:37], v[36:37], 0.5 op_sel_hi:[1,0]
	v_pk_add_f32 v[46:47], v[46:47], 1.0 op_sel_hi:[1,0]
	s_nop 0
	v_pk_mul_f32 v[42:43], v[42:43], v[46:47]
	v_lshl_add_u64 v[46:47], v[62:63], 0, v[40:41]
	v_pk_add_f32 v[62:63], v[70:71], 1.0 op_sel_hi:[1,0]
	v_cvt_pk_bf16_f32 v45, v42, v43
	global_store_dwordx2 v[46:47], v[44:45], off
	v_rcp_f32_e32 v43, v63
	s_nop 0
	v_add_f32_e32 v43, v43, v43
	v_mul_f32_e32 v44, 0x3d372713, v38
	v_mul_f32_e32 v45, 0x3d372713, v39
	v_mul_f32_e32 v44, v38, v44
	v_mul_f32_e32 v45, v39, v45
	v_fma_f32 v44, v38, v44, v38
	v_fma_f32 v45, v39, v45, v39
	v_mul_f32_e32 v44, 0x3f4c422a, v44
	v_mul_f32_e32 v45, 0x3f4c422a, v45
	v_add_f32_e32 v44, v44, v44
	v_add_f32_e32 v45, v45, v45
	v_mul_f32_e32 v44, 0x3fb8aa3b, v44
	v_mul_f32_e32 v45, 0x3fb8aa3b, v45
	v_exp_f32_e32 v44, v44
	v_exp_f32_e32 v45, v45
	v_rcp_f32_e32 v42, v62
	s_nop 0
	v_add_f32_e32 v42, v42, v42
	v_pk_add_f32 v[42:43], v[42:43], 1.0 op_sel_hi:[1,0] neg_lo:[1,0] neg_hi:[1,0]
	v_pk_add_f32 v[44:45], v[44:45], 1.0 op_sel_hi:[1,0]
	v_pk_add_f32 v[42:43], v[42:43], 1.0 op_sel_hi:[1,0]
	v_pk_mul_f32 v[36:37], v[36:37], v[42:43]
	v_pk_mul_f32 v[38:39], v[38:39], 0.5 op_sel_hi:[1,0]
	v_cvt_pk_bf16_f32 v36, v36, v37
	v_rcp_f32_e32 v43, v45
	s_nop 0
	v_add_f32_e32 v43, v43, v43
	v_rcp_f32_e32 v42, v44
	s_nop 0
	v_add_f32_e32 v42, v42, v42
	v_mul_f32_e32 v44, 0x3d372713, v32
	v_mul_f32_e32 v45, 0x3d372713, v33
	v_mul_f32_e32 v44, v32, v44
	v_mul_f32_e32 v45, v33, v45
	v_fma_f32 v44, v32, v44, v32
	v_fma_f32 v45, v33, v45, v33
	v_mul_f32_e32 v44, 0x3f4c422a, v44
	v_mul_f32_e32 v45, 0x3f4c422a, v45
	v_add_f32_e32 v44, v44, v44
	v_add_f32_e32 v45, v45, v45
	v_mul_f32_e32 v44, 0x3fb8aa3b, v44
	v_mul_f32_e32 v45, 0x3fb8aa3b, v45
	v_exp_f32_e32 v44, v44
	v_exp_f32_e32 v45, v45
	v_pk_add_f32 v[42:43], v[42:43], 1.0 op_sel_hi:[1,0] neg_lo:[1,0] neg_hi:[1,0]
	v_pk_mul_f32 v[32:33], v[32:33], 0.5 op_sel_hi:[1,0]
	v_pk_add_f32 v[42:43], v[42:43], 1.0 op_sel_hi:[1,0]
	v_pk_add_f32 v[44:45], v[44:45], 1.0 op_sel_hi:[1,0]
	v_pk_mul_f32 v[38:39], v[38:39], v[42:43]
	v_lshl_add_u64 v[42:43], v[58:59], 0, v[40:41]
	v_cvt_pk_bf16_f32 v37, v38, v39
	global_store_dwordx2 v[42:43], v[36:37], off
	v_rcp_f32_e32 v37, v45
	s_nop 0
	v_add_f32_e32 v37, v37, v37
	v_mul_f32_e32 v38, 0x3d372713, v34
	v_mul_f32_e32 v39, 0x3d372713, v35
	v_mul_f32_e32 v38, v34, v38
	v_mul_f32_e32 v39, v35, v39
	v_fma_f32 v38, v34, v38, v34
	v_fma_f32 v39, v35, v39, v35
	v_mul_f32_e32 v38, 0x3f4c422a, v38
	v_mul_f32_e32 v39, 0x3f4c422a, v39
	v_add_f32_e32 v38, v38, v38
	v_add_f32_e32 v39, v39, v39
	v_mul_f32_e32 v38, 0x3fb8aa3b, v38
	v_mul_f32_e32 v39, 0x3fb8aa3b, v39
	v_exp_f32_e32 v38, v38
	v_exp_f32_e32 v39, v39
	v_rcp_f32_e32 v36, v44
	s_nop 0
	v_add_f32_e32 v36, v36, v36
	v_pk_add_f32 v[36:37], v[36:37], 1.0 op_sel_hi:[1,0] neg_lo:[1,0] neg_hi:[1,0]
	v_pk_add_f32 v[38:39], v[38:39], 1.0 op_sel_hi:[1,0]
	v_pk_add_f32 v[36:37], v[36:37], 1.0 op_sel_hi:[1,0]
	v_pk_mul_f32 v[32:33], v[32:33], v[36:37]
	v_pk_mul_f32 v[34:35], v[34:35], 0.5 op_sel_hi:[1,0]
	v_cvt_pk_bf16_f32 v32, v32, v33
	v_rcp_f32_e32 v37, v39
	s_nop 0
	v_add_f32_e32 v37, v37, v37
	v_rcp_f32_e32 v36, v38
	s_nop 0
	v_add_f32_e32 v36, v36, v36
	v_pk_add_f32 v[36:37], v[36:37], 1.0 op_sel_hi:[1,0] neg_lo:[1,0] neg_hi:[1,0]
	s_nop 0
	v_pk_add_f32 v[36:37], v[36:37], 1.0 op_sel_hi:[1,0]
	s_nop 0
	v_pk_mul_f32 v[34:35], v[34:35], v[36:37]
	v_lshl_add_u64 v[36:37], v[54:55], 0, v[40:41]
	v_cvt_pk_bf16_f32 v33, v34, v35
	global_store_dwordx2 v[36:37], v[32:33], off
	global_load_dwordx4 v[32:35], v[68:69], off offset:128
	v_or_b32_e32 v40, 32, v72
	v_ashrrev_i32_e32 v40, 5, v40
	s_waitcnt vmcnt(0)
; DI void store4(u16* dst, f32x4 v) { uint2 w; w.x = cvtpk(v[0], v[1]); w.y = cvtpk(v[2], v[3]); *(uint2*)dst = w; }
; DI void phase2(const Params& p, int bid, int nblk, unsigned char* smem) {
;     ...
;         for (int mi = 0; mi < 4; ++mi) {
;           const int f = fb + mi * 16 + lq * 4; const float4 bb = *(const float4*)(b1 + f);
; #pragma unroll
;           for (int ni = 0; ni < 4; ++ni) {
;             const int t = tb + ni * 16 + lr; f32x4 v = acc[mi][ni]; v[0] += bb.x; v[1] += bb.y; v[2] += bb.z; v[3] += bb.w;
; #pragma unroll
;             for (int j = 0; j < 4; ++j) { const float xx = v[j]; const float u = 0.7978845608028654f * (xx + 0.044715f * xx * xx * xx); const float th = 1.0f - 2.0f / (__expf(2.0f * u) + 1.0f); v[j] = 0.5f * xx * (1.0f + th); }
;             store4(hid + ((size_t)(f >> 5) * CROWS + t) * 32 + (f & 31), v);
;           }
	v_pk_add_f32 v[28:29], v[28:29], v[32:33]
	s_nop 0
	v_mul_f32_e32 v36, 0x3d372713, v28
	v_mul_f32_e32 v37, 0x3d372713, v29
	v_mul_f32_e32 v36, v28, v36
	v_mul_f32_e32 v37, v29, v37
	v_fma_f32 v36, v28, v36, v28
	v_fma_f32 v37, v29, v37, v29
	v_mul_f32_e32 v36, 0x3f4c422a, v36
	v_mul_f32_e32 v37, 0x3f4c422a, v37
	v_add_f32_e32 v36, v36, v36
	v_add_f32_e32 v37, v37, v37
	v_mul_f32_e32 v36, 0x3fb8aa3b, v36
	v_mul_f32_e32 v37, 0x3fb8aa3b, v37
	v_exp_f32_e32 v36, v36
	v_exp_f32_e32 v37, v37
	v_pk_add_f32 v[30:31], v[30:31], v[34:35]
	v_pk_mul_f32 v[28:29], v[28:29], 0.5 op_sel_hi:[1,0]
	v_pk_add_f32 v[24:25], v[24:25], v[32:33]
	v_pk_add_f32 v[36:37], v[36:37], 1.0 op_sel_hi:[1,0]
	v_pk_add_f32 v[26:27], v[26:27], v[34:35]
	v_pk_add_f32 v[20:21], v[20:21], v[32:33]
	v_pk_add_f32 v[22:23], v[22:23], v[34:35]
	v_pk_add_f32 v[16:17], v[16:17], v[32:33]
	v_rcp_f32_e32 v37, v37
	s_nop 0
	v_add_f32_e32 v37, v37, v37
	v_pk_add_f32 v[18:19], v[18:19], v[34:35]
	v_mul_f32_e32 v38, 0x3d372713, v30
	v_mul_f32_e32 v39, 0x3d372713, v31
	v_mul_f32_e32 v38, v30, v38
	v_mul_f32_e32 v39, v31, v39
	v_fma_f32 v38, v30, v38, v30
	v_fma_f32 v39, v31, v39, v31
	v_mul_f32_e32 v38, 0x3f4c422a, v38
	v_mul_f32_e32 v39, 0x3f4c422a, v39
	v_add_f32_e32 v38, v38, v38
	v_add_f32_e32 v39, v39, v39
	v_mul_f32_e32 v38, 0x3fb8aa3b, v38
	v_mul_f32_e32 v39, 0x3fb8aa3b, v39
	v_exp_f32_e32 v38, v38
	v_exp_f32_e32 v39, v39
	v_rcp_f32_e32 v36, v36
	s_nop 0
	v_add_f32_e32 v36, v36, v36
	v_pk_add_f32 v[36:37], v[36:37], 1.0 op_sel_hi:[1,0] neg_lo:[1,0] neg_hi:[1,0]
	v_pk_add_f32 v[38:39], v[38:39], 1.0 op_sel_hi:[1,0]
	v_pk_add_f32 v[36:37], v[36:37], 1.0 op_sel_hi:[1,0]
	v_pk_mul_f32 v[28:29], v[28:29], v[36:37]
	v_pk_mul_f32 v[30:31], v[30:31], 0.5 op_sel_hi:[1,0]
	v_cvt_pk_bf16_f32 v28, v28, v29
	v_rcp_f32_e32 v37, v39
	s_nop 0
	v_add_f32_e32 v37, v37, v37
	v_rcp_f32_e32 v36, v38
	s_nop 0
	v_add_f32_e32 v36, v36, v36
	v_mul_f32_e32 v38, 0x3d372713, v24
	v_mul_f32_e32 v39, 0x3d372713, v25
	v_mul_f32_e32 v38, v24, v38
	v_mul_f32_e32 v39, v25, v39
	v_fma_f32 v38, v24, v38, v24
	v_fma_f32 v39, v25, v39, v25
	v_mul_f32_e32 v38, 0x3f4c422a, v38
	v_mul_f32_e32 v39, 0x3f4c422a, v39
	v_add_f32_e32 v38, v38, v38
	v_add_f32_e32 v39, v39, v39
	v_mul_f32_e32 v38, 0x3fb8aa3b, v38
	v_mul_f32_e32 v39, 0x3fb8aa3b, v39
	v_exp_f32_e32 v38, v38
	v_exp_f32_e32 v39, v39
	v_pk_add_f32 v[36:37], v[36:37], 1.0 op_sel_hi:[1,0] neg_lo:[1,0] neg_hi:[1,0]
	v_pk_mul_f32 v[24:25], v[24:25], 0.5 op_sel_hi:[1,0]
	v_pk_add_f32 v[36:37], v[36:37], 1.0 op_sel_hi:[1,0]
	v_pk_add_f32 v[38:39], v[38:39], 1.0 op_sel_hi:[1,0]
	v_pk_mul_f32 v[30:31], v[30:31], v[36:37]
	v_mad_i64_i32 v[36:37], s[0:1], v40, s52, v[64:65]
	v_lshlrev_b64 v[36:37], 6, v[36:37]
	v_lshl_add_u64 v[36:37], s[20:21], 0, v[36:37]
	v_lshl_add_u64 v[36:37], v[36:37], 0, v[80:81]
	v_cvt_pk_bf16_f32 v29, v30, v31
	global_store_dwordx2 v[36:37], v[28:29], off
	v_rcp_f32_e32 v29, v39
	s_nop 0
	v_add_f32_e32 v29, v29, v29
	v_mul_f32_e32 v30, 0x3d372713, v26
	v_mul_f32_e32 v31, 0x3d372713, v27
	v_mul_f32_e32 v30, v26, v30
	v_mul_f32_e32 v31, v27, v31
	v_fma_f32 v30, v26, v30, v26
	v_fma_f32 v31, v27, v31, v27
	v_mul_f32_e32 v30, 0x3f4c422a, v30
	v_mul_f32_e32 v31, 0x3f4c422a, v31
	v_add_f32_e32 v30, v30, v30
	v_add_f32_e32 v31, v31, v31
	v_mul_f32_e32 v30, 0x3fb8aa3b, v30
	v_mul_f32_e32 v31, 0x3fb8aa3b, v31
	v_exp_f32_e32 v30, v30
	v_exp_f32_e32 v31, v31
	v_rcp_f32_e32 v28, v38
	s_nop 0
	v_add_f32_e32 v28, v28, v28
	v_pk_add_f32 v[28:29], v[28:29], 1.0 op_sel_hi:[1,0] neg_lo:[1,0] neg_hi:[1,0]
	v_pk_add_f32 v[30:31], v[30:31], 1.0 op_sel_hi:[1,0]
	v_pk_add_f32 v[28:29], v[28:29], 1.0 op_sel_hi:[1,0]
	v_pk_mul_f32 v[24:25], v[24:25], v[28:29]
	v_pk_mul_f32 v[26:27], v[26:27], 0.5 op_sel_hi:[1,0]
	v_cvt_pk_bf16_f32 v24, v24, v25
	v_rcp_f32_e32 v29, v31
	s_nop 0
	v_add_f32_e32 v29, v29, v29
	v_rcp_f32_e32 v28, v30
	s_nop 0
	v_add_f32_e32 v28, v28, v28
	v_mul_f32_e32 v30, 0x3d372713, v20
	v_mul_f32_e32 v31, 0x3d372713, v21
	v_mul_f32_e32 v30, v20, v30
	v_mul_f32_e32 v31, v21, v31
	v_fma_f32 v30, v20, v30, v20
	v_fma_f32 v31, v21, v31, v21
	v_mul_f32_e32 v30, 0x3f4c422a, v30
	v_mul_f32_e32 v31, 0x3f4c422a, v31
	v_add_f32_e32 v30, v30, v30
	v_add_f32_e32 v31, v31, v31
	v_mul_f32_e32 v30, 0x3fb8aa3b, v30
	v_mul_f32_e32 v31, 0x3fb8aa3b, v31
	v_exp_f32_e32 v30, v30
	v_exp_f32_e32 v31, v31
	v_pk_add_f32 v[28:29], v[28:29], 1.0 op_sel_hi:[1,0] neg_lo:[1,0] neg_hi:[1,0]
	v_pk_mul_f32 v[20:21], v[20:21], 0.5 op_sel_hi:[1,0]
	v_pk_add_f32 v[28:29], v[28:29], 1.0 op_sel_hi:[1,0]
	v_pk_add_f32 v[30:31], v[30:31], 1.0 op_sel_hi:[1,0]
	v_pk_mul_f32 v[26:27], v[26:27], v[28:29]
	v_mad_i64_i32 v[28:29], s[0:1], v40, s52, v[60:61]
	v_lshlrev_b64 v[28:29], 6, v[28:29]
	v_lshl_add_u64 v[28:29], s[20:21], 0, v[28:29]
	v_lshl_add_u64 v[28:29], v[28:29], 0, v[80:81]
	v_cvt_pk_bf16_f32 v25, v26, v27
	global_store_dwordx2 v[28:29], v[24:25], off
	v_rcp_f32_e32 v25, v31
	s_nop 0
	v_add_f32_e32 v25, v25, v25
	v_mul_f32_e32 v26, 0x3d372713, v22
	v_mul_f32_e32 v27, 0x3d372713, v23
	v_mul_f32_e32 v26, v22, v26
	v_mul_f32_e32 v27, v23, v27
	v_fma_f32 v26, v22, v26, v22
	v_fma_f32 v27, v23, v27, v23
	v_mul_f32_e32 v26, 0x3f4c422a, v26
	v_mul_f32_e32 v27, 0x3f4c422a, v27
	v_add_f32_e32 v26, v26, v26
	v_add_f32_e32 v27, v27, v27
	v_mul_f32_e32 v26, 0x3fb8aa3b, v26
	v_mul_f32_e32 v27, 0x3fb8aa3b, v27
	v_exp_f32_e32 v26, v26
	v_exp_f32_e32 v27, v27
	v_rcp_f32_e32 v24, v30
	s_nop 0
	v_add_f32_e32 v24, v24, v24
	v_pk_add_f32 v[24:25], v[24:25], 1.0 op_sel_hi:[1,0] neg_lo:[1,0] neg_hi:[1,0]
	v_pk_add_f32 v[26:27], v[26:27], 1.0 op_sel_hi:[1,0]
	v_pk_add_f32 v[24:25], v[24:25], 1.0 op_sel_hi:[1,0]
; DI void store4(u16* dst, f32x4 v) { uint2 w; w.x = cvtpk(v[0], v[1]); w.y = cvtpk(v[2], v[3]); *(uint2*)dst = w; }
; DI void phase2(const Params& p, int bid, int nblk, unsigned char* smem) {
;     ...
;         for (int mi = 0; mi < 4; ++mi) {
;           const int f = fb + mi * 16 + lq * 4; const float4 bb = *(const float4*)(b1 + f);
; #pragma unroll
;           for (int ni = 0; ni < 4; ++ni) {
;             const int t = tb + ni * 16 + lr; f32x4 v = acc[mi][ni]; v[0] += bb.x; v[1] += bb.y; v[2] += bb.z; v[3] += bb.w;
; #pragma unroll
;             for (int j = 0; j < 4; ++j) { const float xx = v[j]; const float u = 0.7978845608028654f * (xx + 0.044715f * xx * xx * xx); const float th = 1.0f - 2.0f / (__expf(2.0f * u) + 1.0f); v[j] = 0.5f * xx * (1.0f + th); }
;             store4(hid + ((size_t)(f >> 5) * CROWS + t) * 32 + (f & 31), v);
;           }
	v_pk_mul_f32 v[20:21], v[20:21], v[24:25]
	v_pk_mul_f32 v[22:23], v[22:23], 0.5 op_sel_hi:[1,0]
	v_cvt_pk_bf16_f32 v20, v20, v21
	v_rcp_f32_e32 v25, v27
	s_nop 0
	v_add_f32_e32 v25, v25, v25
	v_rcp_f32_e32 v24, v26
	s_nop 0
	v_add_f32_e32 v24, v24, v24
	v_mul_f32_e32 v26, 0x3d372713, v16
	v_mul_f32_e32 v27, 0x3d372713, v17
	v_mul_f32_e32 v26, v16, v26
	v_mul_f32_e32 v27, v17, v27
	v_fma_f32 v26, v16, v26, v16
	v_fma_f32 v27, v17, v27, v17
	v_mul_f32_e32 v26, 0x3f4c422a, v26
	v_mul_f32_e32 v27, 0x3f4c422a, v27
	v_add_f32_e32 v26, v26, v26
	v_add_f32_e32 v27, v27, v27
	v_mul_f32_e32 v26, 0x3fb8aa3b, v26
	v_mul_f32_e32 v27, 0x3fb8aa3b, v27
	v_exp_f32_e32 v26, v26
	v_exp_f32_e32 v27, v27
	v_pk_add_f32 v[24:25], v[24:25], 1.0 op_sel_hi:[1,0] neg_lo:[1,0] neg_hi:[1,0]
	v_pk_mul_f32 v[16:17], v[16:17], 0.5 op_sel_hi:[1,0]
	v_pk_add_f32 v[24:25], v[24:25], 1.0 op_sel_hi:[1,0]
	v_pk_add_f32 v[26:27], v[26:27], 1.0 op_sel_hi:[1,0]
	v_pk_mul_f32 v[22:23], v[22:23], v[24:25]
	v_mad_i64_i32 v[24:25], s[0:1], v40, s52, v[56:57]
	v_lshlrev_b64 v[24:25], 6, v[24:25]
	v_lshl_add_u64 v[24:25], s[20:21], 0, v[24:25]
	v_lshl_add_u64 v[24:25], v[24:25], 0, v[80:81]
	v_cvt_pk_bf16_f32 v21, v22, v23
	global_store_dwordx2 v[24:25], v[20:21], off
	v_rcp_f32_e32 v21, v27
	s_nop 0
	v_add_f32_e32 v21, v21, v21
	v_mul_f32_e32 v22, 0x3d372713, v18
	v_mul_f32_e32 v23, 0x3d372713, v19
	v_mul_f32_e32 v22, v18, v22
	v_mul_f32_e32 v23, v19, v23
	v_fma_f32 v22, v18, v22, v18
	v_fma_f32 v23, v19, v23, v19
	v_mul_f32_e32 v22, 0x3f4c422a, v22
	v_mul_f32_e32 v23, 0x3f4c422a, v23
	v_add_f32_e32 v22, v22, v22
	v_add_f32_e32 v23, v23, v23
	v_mul_f32_e32 v22, 0x3fb8aa3b, v22
	v_mul_f32_e32 v23, 0x3fb8aa3b, v23
	v_exp_f32_e32 v22, v22
	v_exp_f32_e32 v23, v23
	v_rcp_f32_e32 v20, v26
	s_nop 0
	v_add_f32_e32 v20, v20, v20
	v_pk_add_f32 v[20:21], v[20:21], 1.0 op_sel_hi:[1,0] neg_lo:[1,0] neg_hi:[1,0]
	v_pk_add_f32 v[22:23], v[22:23], 1.0 op_sel_hi:[1,0]
	v_pk_add_f32 v[20:21], v[20:21], 1.0 op_sel_hi:[1,0]
	v_pk_mul_f32 v[16:17], v[16:17], v[20:21]
	v_pk_mul_f32 v[18:19], v[18:19], 0.5 op_sel_hi:[1,0]
	v_cvt_pk_bf16_f32 v16, v16, v17
	v_rcp_f32_e32 v21, v23
	s_nop 0
	v_add_f32_e32 v21, v21, v21
	v_rcp_f32_e32 v20, v22
	s_nop 0
	v_add_f32_e32 v20, v20, v20
	v_pk_add_f32 v[20:21], v[20:21], 1.0 op_sel_hi:[1,0] neg_lo:[1,0] neg_hi:[1,0]
	v_or_b32_e32 v24, 48, v66
	v_pk_add_f32 v[20:21], v[20:21], 1.0 op_sel_hi:[1,0]
	v_bitop3_b32 v25, v66, 28, 48 bitop3:0xc8
	v_pk_mul_f32 v[18:19], v[18:19], v[20:21]
	v_mad_i64_i32 v[20:21], s[0:1], v40, s52, v[52:53]
	v_lshlrev_b64 v[20:21], 6, v[20:21]
	v_lshl_add_u64 v[20:21], s[20:21], 0, v[20:21]
	v_lshl_add_u64 v[20:21], v[20:21], 0, v[80:81]
	v_cvt_pk_bf16_f32 v17, v18, v19
	global_store_dwordx2 v[20:21], v[16:17], off
	global_load_dwordx4 v[16:19], v[68:69], off offset:192
	v_ashrrev_i32_e32 v24, 5, v24
	v_lshlrev_b32_e32 v80, 1, v25
	s_waitcnt vmcnt(0)
	v_pk_add_f32 v[12:13], v[12:13], v[16:17]
	s_nop 0
	v_mul_f32_e32 v20, 0x3d372713, v12
	v_mul_f32_e32 v21, 0x3d372713, v13
	v_mul_f32_e32 v20, v12, v20
	v_mul_f32_e32 v21, v13, v21
	v_fma_f32 v20, v12, v20, v12
	v_fma_f32 v21, v13, v21, v13
	v_mul_f32_e32 v20, 0x3f4c422a, v20
	v_mul_f32_e32 v21, 0x3f4c422a, v21
	v_add_f32_e32 v20, v20, v20
	v_add_f32_e32 v21, v21, v21
	v_mul_f32_e32 v20, 0x3fb8aa3b, v20
	v_mul_f32_e32 v21, 0x3fb8aa3b, v21
	v_exp_f32_e32 v20, v20
	v_exp_f32_e32 v21, v21
	v_pk_add_f32 v[14:15], v[14:15], v[18:19]
	v_pk_mul_f32 v[12:13], v[12:13], 0.5 op_sel_hi:[1,0]
	v_pk_add_f32 v[8:9], v[8:9], v[16:17]
	v_pk_add_f32 v[20:21], v[20:21], 1.0 op_sel_hi:[1,0]
	v_pk_add_f32 v[10:11], v[10:11], v[18:19]
	v_pk_add_f32 v[4:5], v[4:5], v[16:17]
	v_pk_add_f32 v[6:7], v[6:7], v[18:19]
	v_pk_add_f32 v[0:1], v[0:1], v[16:17]
	v_rcp_f32_e32 v21, v21
	s_nop 0
	v_add_f32_e32 v21, v21, v21
	v_pk_add_f32 v[2:3], v[2:3], v[18:19]
	v_mul_f32_e32 v22, 0x3d372713, v14
	v_mul_f32_e32 v23, 0x3d372713, v15
	v_mul_f32_e32 v22, v14, v22
	v_mul_f32_e32 v23, v15, v23
	v_fma_f32 v22, v14, v22, v14
	v_fma_f32 v23, v15, v23, v15
	v_mul_f32_e32 v22, 0x3f4c422a, v22
	v_mul_f32_e32 v23, 0x3f4c422a, v23
	v_add_f32_e32 v22, v22, v22
	v_add_f32_e32 v23, v23, v23
	v_mul_f32_e32 v22, 0x3fb8aa3b, v22
	v_mul_f32_e32 v23, 0x3fb8aa3b, v23
	v_exp_f32_e32 v22, v22
	v_exp_f32_e32 v23, v23
	v_rcp_f32_e32 v20, v20
	s_nop 0
	v_add_f32_e32 v20, v20, v20
	v_pk_add_f32 v[20:21], v[20:21], 1.0 op_sel_hi:[1,0] neg_lo:[1,0] neg_hi:[1,0]
	v_pk_add_f32 v[22:23], v[22:23], 1.0 op_sel_hi:[1,0]
	v_pk_add_f32 v[20:21], v[20:21], 1.0 op_sel_hi:[1,0]
	v_pk_mul_f32 v[12:13], v[12:13], v[20:21]
	v_pk_mul_f32 v[14:15], v[14:15], 0.5 op_sel_hi:[1,0]
	v_cvt_pk_bf16_f32 v12, v12, v13
	v_rcp_f32_e32 v21, v23
	s_nop 0
	v_add_f32_e32 v21, v21, v21
	v_rcp_f32_e32 v20, v22
	s_nop 0
	v_add_f32_e32 v20, v20, v20
	v_mul_f32_e32 v22, 0x3d372713, v8
	v_mul_f32_e32 v23, 0x3d372713, v9
	v_mul_f32_e32 v22, v8, v22
	v_mul_f32_e32 v23, v9, v23
	v_fma_f32 v22, v8, v22, v8
	v_fma_f32 v23, v9, v23, v9
	v_mul_f32_e32 v22, 0x3f4c422a, v22
	v_mul_f32_e32 v23, 0x3f4c422a, v23
	v_add_f32_e32 v22, v22, v22
	v_add_f32_e32 v23, v23, v23
	v_mul_f32_e32 v22, 0x3fb8aa3b, v22
	v_mul_f32_e32 v23, 0x3fb8aa3b, v23
	v_exp_f32_e32 v22, v22
	v_exp_f32_e32 v23, v23
	v_pk_add_f32 v[20:21], v[20:21], 1.0 op_sel_hi:[1,0] neg_lo:[1,0] neg_hi:[1,0]
	v_pk_mul_f32 v[8:9], v[8:9], 0.5 op_sel_hi:[1,0]
	v_pk_add_f32 v[20:21], v[20:21], 1.0 op_sel_hi:[1,0]
	v_pk_add_f32 v[22:23], v[22:23], 1.0 op_sel_hi:[1,0]
	v_pk_mul_f32 v[14:15], v[14:15], v[20:21]
; DI void store4(u16* dst, f32x4 v) { uint2 w; w.x = cvtpk(v[0], v[1]); w.y = cvtpk(v[2], v[3]); *(uint2*)dst = w; }
; DI void phase2(const Params& p, int bid, int nblk, unsigned char* smem) {
;     ...
;         for (int mi = 0; mi < 4; ++mi) {
;           const int f = fb + mi * 16 + lq * 4; const float4 bb = *(const float4*)(b1 + f);
; #pragma unroll
;           for (int ni = 0; ni < 4; ++ni) {
;             const int t = tb + ni * 16 + lr; f32x4 v = acc[mi][ni]; v[0] += bb.x; v[1] += bb.y; v[2] += bb.z; v[3] += bb.w;
; #pragma unroll
;             for (int j = 0; j < 4; ++j) { const float xx = v[j]; const float u = 0.7978845608028654f * (xx + 0.044715f * xx * xx * xx); const float th = 1.0f - 2.0f / (__expf(2.0f * u) + 1.0f); v[j] = 0.5f * xx * (1.0f + th); }
;             store4(hid + ((size_t)(f >> 5) * CROWS + t) * 32 + (f & 31), v);
;           }
	v_mad_i64_i32 v[20:21], s[0:1], v24, s52, v[64:65]
	v_lshlrev_b64 v[20:21], 6, v[20:21]
	v_lshl_add_u64 v[20:21], s[20:21], 0, v[20:21]
	v_lshl_add_u64 v[20:21], v[20:21], 0, v[80:81]
	v_cvt_pk_bf16_f32 v13, v14, v15
	global_store_dwordx2 v[20:21], v[12:13], off
	v_rcp_f32_e32 v13, v23
	s_nop 0
	v_add_f32_e32 v13, v13, v13
	v_mul_f32_e32 v14, 0x3d372713, v10
	v_mul_f32_e32 v15, 0x3d372713, v11
	v_mul_f32_e32 v14, v10, v14
	v_mul_f32_e32 v15, v11, v15
	v_fma_f32 v14, v10, v14, v10
	v_fma_f32 v15, v11, v15, v11
	v_mul_f32_e32 v14, 0x3f4c422a, v14
	v_mul_f32_e32 v15, 0x3f4c422a, v15
	v_add_f32_e32 v14, v14, v14
	v_add_f32_e32 v15, v15, v15
	v_mul_f32_e32 v14, 0x3fb8aa3b, v14
	v_mul_f32_e32 v15, 0x3fb8aa3b, v15
	v_exp_f32_e32 v14, v14
	v_exp_f32_e32 v15, v15
	v_rcp_f32_e32 v12, v22
	s_nop 0
	v_add_f32_e32 v12, v12, v12
	v_pk_add_f32 v[12:13], v[12:13], 1.0 op_sel_hi:[1,0] neg_lo:[1,0] neg_hi:[1,0]
	v_pk_add_f32 v[14:15], v[14:15], 1.0 op_sel_hi:[1,0]
	v_pk_add_f32 v[12:13], v[12:13], 1.0 op_sel_hi:[1,0]
	v_pk_mul_f32 v[8:9], v[8:9], v[12:13]
	v_pk_mul_f32 v[10:11], v[10:11], 0.5 op_sel_hi:[1,0]
	v_cvt_pk_bf16_f32 v8, v8, v9
	v_rcp_f32_e32 v13, v15
	s_nop 0
	v_add_f32_e32 v13, v13, v13
	v_rcp_f32_e32 v12, v14
	s_nop 0
	v_add_f32_e32 v12, v12, v12
	v_mul_f32_e32 v14, 0x3d372713, v4
	v_mul_f32_e32 v15, 0x3d372713, v5
	v_mul_f32_e32 v14, v4, v14
	v_mul_f32_e32 v15, v5, v15
	v_fma_f32 v14, v4, v14, v4
	v_fma_f32 v15, v5, v15, v5
	v_mul_f32_e32 v14, 0x3f4c422a, v14
	v_mul_f32_e32 v15, 0x3f4c422a, v15
	v_add_f32_e32 v14, v14, v14
	v_add_f32_e32 v15, v15, v15
	v_mul_f32_e32 v14, 0x3fb8aa3b, v14
	v_mul_f32_e32 v15, 0x3fb8aa3b, v15
	v_exp_f32_e32 v14, v14
	v_exp_f32_e32 v15, v15
	v_pk_add_f32 v[12:13], v[12:13], 1.0 op_sel_hi:[1,0] neg_lo:[1,0] neg_hi:[1,0]
	v_pk_mul_f32 v[4:5], v[4:5], 0.5 op_sel_hi:[1,0]
	v_pk_add_f32 v[12:13], v[12:13], 1.0 op_sel_hi:[1,0]
	v_pk_add_f32 v[14:15], v[14:15], 1.0 op_sel_hi:[1,0]
	v_pk_mul_f32 v[10:11], v[10:11], v[12:13]
	v_mad_i64_i32 v[12:13], s[0:1], v24, s52, v[60:61]
	v_lshlrev_b64 v[12:13], 6, v[12:13]
	v_lshl_add_u64 v[12:13], s[20:21], 0, v[12:13]
	v_lshl_add_u64 v[12:13], v[12:13], 0, v[80:81]
	v_cvt_pk_bf16_f32 v9, v10, v11
	global_store_dwordx2 v[12:13], v[8:9], off
	v_rcp_f32_e32 v9, v15
	s_nop 0
	v_add_f32_e32 v9, v9, v9
	v_mul_f32_e32 v10, 0x3d372713, v6
	v_mul_f32_e32 v11, 0x3d372713, v7
	v_mul_f32_e32 v10, v6, v10
	v_mul_f32_e32 v11, v7, v11
	v_fma_f32 v10, v6, v10, v6
	v_fma_f32 v11, v7, v11, v7
	v_mul_f32_e32 v10, 0x3f4c422a, v10
	v_mul_f32_e32 v11, 0x3f4c422a, v11
	v_add_f32_e32 v10, v10, v10
	v_add_f32_e32 v11, v11, v11
	v_mul_f32_e32 v10, 0x3fb8aa3b, v10
	v_mul_f32_e32 v11, 0x3fb8aa3b, v11
	v_exp_f32_e32 v10, v10
	v_exp_f32_e32 v11, v11
	v_rcp_f32_e32 v8, v14
	s_nop 0
	v_add_f32_e32 v8, v8, v8
	v_pk_add_f32 v[8:9], v[8:9], 1.0 op_sel_hi:[1,0] neg_lo:[1,0] neg_hi:[1,0]
	v_pk_add_f32 v[10:11], v[10:11], 1.0 op_sel_hi:[1,0]
	v_pk_add_f32 v[8:9], v[8:9], 1.0 op_sel_hi:[1,0]
	v_pk_mul_f32 v[4:5], v[4:5], v[8:9]
	v_pk_mul_f32 v[6:7], v[6:7], 0.5 op_sel_hi:[1,0]
	v_cvt_pk_bf16_f32 v4, v4, v5
	v_rcp_f32_e32 v9, v11
	s_nop 0
	v_add_f32_e32 v9, v9, v9
	v_rcp_f32_e32 v8, v10
	s_nop 0
	v_add_f32_e32 v8, v8, v8
	v_mul_f32_e32 v10, 0x3d372713, v0
	v_mul_f32_e32 v11, 0x3d372713, v1
	v_mul_f32_e32 v10, v0, v10
	v_mul_f32_e32 v11, v1, v11
	v_fma_f32 v10, v0, v10, v0
	v_fma_f32 v11, v1, v11, v1
	v_mul_f32_e32 v10, 0x3f4c422a, v10
	v_mul_f32_e32 v11, 0x3f4c422a, v11
	v_add_f32_e32 v10, v10, v10
	v_add_f32_e32 v11, v11, v11
	v_mul_f32_e32 v10, 0x3fb8aa3b, v10
	v_mul_f32_e32 v11, 0x3fb8aa3b, v11
	v_exp_f32_e32 v10, v10
	v_exp_f32_e32 v11, v11
	v_pk_add_f32 v[8:9], v[8:9], 1.0 op_sel_hi:[1,0] neg_lo:[1,0] neg_hi:[1,0]
	v_pk_mul_f32 v[0:1], v[0:1], 0.5 op_sel_hi:[1,0]
	v_pk_add_f32 v[8:9], v[8:9], 1.0 op_sel_hi:[1,0]
	v_pk_add_f32 v[10:11], v[10:11], 1.0 op_sel_hi:[1,0]
	v_pk_mul_f32 v[6:7], v[6:7], v[8:9]
	v_mad_i64_i32 v[8:9], s[0:1], v24, s52, v[56:57]
	v_lshlrev_b64 v[8:9], 6, v[8:9]
	v_lshl_add_u64 v[8:9], s[20:21], 0, v[8:9]
	v_lshl_add_u64 v[8:9], v[8:9], 0, v[80:81]
	v_cvt_pk_bf16_f32 v5, v6, v7
	global_store_dwordx2 v[8:9], v[4:5], off
	v_rcp_f32_e32 v5, v11
	s_nop 0
	v_add_f32_e32 v5, v5, v5
	v_mul_f32_e32 v6, 0x3d372713, v2
	v_mul_f32_e32 v7, 0x3d372713, v3
	v_mul_f32_e32 v6, v2, v6
	v_mul_f32_e32 v7, v3, v7
	v_fma_f32 v6, v2, v6, v2
	v_fma_f32 v7, v3, v7, v3
	v_mul_f32_e32 v6, 0x3f4c422a, v6
	v_mul_f32_e32 v7, 0x3f4c422a, v7
	v_add_f32_e32 v6, v6, v6
	v_add_f32_e32 v7, v7, v7
	v_mul_f32_e32 v6, 0x3fb8aa3b, v6
	v_mul_f32_e32 v7, 0x3fb8aa3b, v7
	v_exp_f32_e32 v6, v6
	v_exp_f32_e32 v7, v7
	v_rcp_f32_e32 v4, v10
	s_nop 0
	v_add_f32_e32 v4, v4, v4
	v_pk_add_f32 v[4:5], v[4:5], 1.0 op_sel_hi:[1,0] neg_lo:[1,0] neg_hi:[1,0]
	v_pk_add_f32 v[6:7], v[6:7], 1.0 op_sel_hi:[1,0]
	v_pk_add_f32 v[4:5], v[4:5], 1.0 op_sel_hi:[1,0]
	v_pk_mul_f32 v[0:1], v[0:1], v[4:5]
	v_pk_mul_f32 v[2:3], v[2:3], 0.5 op_sel_hi:[1,0]
	v_cvt_pk_bf16_f32 v0, v0, v1
	v_rcp_f32_e32 v5, v7
	s_nop 0
	v_add_f32_e32 v5, v5, v5
	v_rcp_f32_e32 v4, v6
	s_nop 0
	v_add_f32_e32 v4, v4, v4
	v_pk_add_f32 v[4:5], v[4:5], 1.0 op_sel_hi:[1,0] neg_lo:[1,0] neg_hi:[1,0]
	s_nop 0
	v_pk_add_f32 v[4:5], v[4:5], 1.0 op_sel_hi:[1,0]
	s_nop 0
	v_pk_mul_f32 v[2:3], v[2:3], v[4:5]
	v_mad_i64_i32 v[4:5], s[0:1], v24, s52, v[52:53]
	v_lshlrev_b64 v[4:5], 6, v[4:5]
	v_lshl_add_u64 v[4:5], s[20:21], 0, v[4:5]
	v_lshl_add_u64 v[4:5], v[4:5], 0, v[80:81]
	v_cvt_pk_bf16_f32 v1, v2, v3
	global_store_dwordx2 v[4:5], v[0:1], off
	s_branch .LBB0_335

; DI f32x4 mfma16(bf16x8 a, bf16x8 b, f32x4 c) { return __builtin_amdgcn_mfma_f32_16x16x32_bf16(a, b, c, 0, 0, 0); }
; template <int NI, class XL, class EP>
; DI void gemm_tile(const u16* __restrict__ W, int ldw, int f0, int t0, int K, XL xl, EP ep, unsigned char* smem) {
;     ...
;   for (int it = 0; it < nk; ++it) {
;     const u16* Ws = S0 + (it & 1) * BUF; const u16* Xs = Ws + 128 * LST;
;     __builtin_amdgcn_s_setprio(1);
;     bf16x8 a[4];
; #pragma unroll
;     for (int mi = 0; mi < 4; ++mi) a[mi] = *(const bf16x8*)(Ws + (wf * 64 + mi * 16 + lr) * LST + lq * 8);
; #pragma unroll
;     for (int ni = 0; ni < NI; ++ni) {
;       const bf16x8 b = *(const bf16x8*)(Xs + (wt * (NI * 16) + ni * 16 + lr) * LST + lq * 8);
; #pragma unroll
;       for (int mi = 0; mi < 4; ++mi) acc[mi][ni] = mfma16(a[mi], b, acc[mi][ni]);
;     }
;     __builtin_amdgcn_sched_group_barrier(0x100, 6, 0);
; #pragma unroll
;     for (int ni = 0; ni < NI; ++ni) { __builtin_amdgcn_sched_group_barrier(0x008, 4, 0); if (ni + 2 < NI) __builtin_amdgcn_sched_group_barrier(0x100, 1, 0); }
;     __builtin_amdgcn_s_setprio(0);
;     if (it + 1 < nk) lstore((it + 1) & 1);
;     if (it + 2 < nk) gload(it + 2);
;     __syncthreads();
.LBB0_945:
	s_setprio 1
	ds_read_b128 v[176:179], v228 offset:0
	ds_read_b128 v[180:183], v228 offset:1536
	ds_read_b128 v[188:191], v228 offset:3072
	ds_read_b128 v[192:195], v228 offset:4608
	ds_read_b128 v[184:187], v152 offset:12288
	ds_read_b128 v[196:199], v152 offset:13824
	s_waitcnt lgkmcnt(1)
	v_mfma_f32_16x16x32_bf16 v[148:151], v[176:179], v[184:187], v[148:151]
	v_mfma_f32_16x16x32_bf16 v[136:139], v[180:183], v[184:187], v[136:139]
	v_mfma_f32_16x16x32_bf16 v[112:115], v[188:191], v[184:187], v[112:115]
	v_mfma_f32_16x16x32_bf16 v[80:83], v[192:195], v[184:187], v[80:83]
	ds_read_b128 v[184:187], v152 offset:15360
	s_waitcnt vmcnt(6)
	ds_write_b128 v229, v[20:23] offset:36864
	s_waitcnt lgkmcnt(2)
	v_mfma_f32_16x16x32_bf16 v[144:147], v[176:179], v[196:199], v[144:147]
	v_mfma_f32_16x16x32_bf16 v[128:131], v[180:183], v[196:199], v[128:131]
	v_mfma_f32_16x16x32_bf16 v[100:103], v[188:191], v[196:199], v[100:103]
	v_mfma_f32_16x16x32_bf16 v[52:55], v[192:195], v[196:199], v[52:55]
	ds_read_b128 v[196:199], v152 offset:16896
	ds_write_b128 v229, v[16:19] offset:36960
	global_load_dwordx4 v[20:23], v156, s[98:99]
	global_load_dwordx4 v[16:19], v156, s[98:99] offset:64
	s_waitcnt lgkmcnt(3)
	v_mfma_f32_16x16x32_bf16 v[140:143], v[176:179], v[184:187], v[140:143]
	v_mfma_f32_16x16x32_bf16 v[120:123], v[180:183], v[184:187], v[120:123]
	v_mfma_f32_16x16x32_bf16 v[88:91], v[188:191], v[184:187], v[88:91]
	v_mfma_f32_16x16x32_bf16 v[44:47], v[192:195], v[184:187], v[44:47]
	ds_read_b128 v[184:187], v152 offset:18432
	ds_write_b128 v230, v[36:39] offset:49152
	global_load_dwordx4 v[36:39], v158, s[100:101] offset:2048
	s_waitcnt lgkmcnt(3)
	v_mfma_f32_16x16x32_bf16 v[132:135], v[176:179], v[196:199], v[132:135]
	v_mfma_f32_16x16x32_bf16 v[108:111], v[180:183], v[196:199], v[108:111]
	v_mfma_f32_16x16x32_bf16 v[76:79], v[188:191], v[196:199], v[76:79]
	v_mfma_f32_16x16x32_bf16 v[40:43], v[192:195], v[196:199], v[40:43]
	ds_read_b128 v[196:199], v152 offset:19968
	ds_write_b128 v230, v[32:35] offset:49248
	global_load_dwordx4 v[32:35], v158, s[100:101] offset:2112
	s_waitcnt lgkmcnt(3)
	v_mfma_f32_16x16x32_bf16 v[124:127], v[176:179], v[184:187], v[124:127]
	v_mfma_f32_16x16x32_bf16 v[96:99], v[180:183], v[184:187], v[96:99]
	v_mfma_f32_16x16x32_bf16 v[68:71], v[188:191], v[184:187], v[68:71]
	v_mfma_f32_16x16x32_bf16 v[12:15], v[192:195], v[184:187], v[12:15]
	ds_read_b128 v[184:187], v152 offset:21504
	ds_write_b128 v230, v[28:31] offset:49344
	global_load_dwordx4 v[28:31], v158, s[100:101] offset:2176
	s_waitcnt lgkmcnt(3)
	v_mfma_f32_16x16x32_bf16 v[116:119], v[176:179], v[196:199], v[116:119]
	v_mfma_f32_16x16x32_bf16 v[84:87], v[180:183], v[196:199], v[84:87]
	v_mfma_f32_16x16x32_bf16 v[60:63], v[188:191], v[196:199], v[60:63]
	v_mfma_f32_16x16x32_bf16 v[8:11], v[192:195], v[196:199], v[8:11]
	ds_read_b128 v[196:199], v152 offset:23040
	ds_write_b128 v230, v[24:27] offset:49440
	global_load_dwordx4 v[24:27], v158, s[100:101] offset:2240
	s_waitcnt lgkmcnt(3)
	v_mfma_f32_16x16x32_bf16 v[104:107], v[176:179], v[184:187], v[104:107]
	v_mfma_f32_16x16x32_bf16 v[72:75], v[180:183], v[184:187], v[72:75]
	v_mfma_f32_16x16x32_bf16 v[56:59], v[188:191], v[184:187], v[56:59]
	v_mfma_f32_16x16x32_bf16 v[4:7], v[192:195], v[184:187], v[4:7]
	s_add_u32 s98, s98, s28
	s_addc_u32 s99, s99, s29
	s_add_u32 s100, s100, s26
	s_addc_u32 s101, s101, s27
	s_waitcnt lgkmcnt(1)
	v_mfma_f32_16x16x32_bf16 v[92:95], v[176:179], v[196:199], v[92:95]
	v_mfma_f32_16x16x32_bf16 v[64:67], v[180:183], v[196:199], v[64:67]
	v_mfma_f32_16x16x32_bf16 v[48:51], v[188:191], v[196:199], v[48:51]
	v_mfma_f32_16x16x32_bf16 v[0:3], v[192:195], v[196:199], v[0:3]
	s_setprio 0
	s_waitcnt lgkmcnt(0)
	s_barrier
	s_setprio 1
	ds_read_b128 v[176:179], v228 offset:36864
	ds_read_b128 v[180:183], v228 offset:38400
	ds_read_b128 v[188:191], v228 offset:39936
	ds_read_b128 v[192:195], v228 offset:41472
	ds_read_b128 v[184:187], v152 offset:49152
	ds_read_b128 v[196:199], v152 offset:50688
	s_waitcnt lgkmcnt(1)
	v_mfma_f32_16x16x32_bf16 v[148:151], v[176:179], v[184:187], v[148:151]
	v_mfma_f32_16x16x32_bf16 v[136:139], v[180:183], v[184:187], v[136:139]
	v_mfma_f32_16x16x32_bf16 v[112:115], v[188:191], v[184:187], v[112:115]
	v_mfma_f32_16x16x32_bf16 v[80:83], v[192:195], v[184:187], v[80:83]
	ds_read_b128 v[184:187], v152 offset:52224
	s_waitcnt vmcnt(6)
	ds_write_b128 v229, v[200:203] offset:0
	s_waitcnt lgkmcnt(2)
	v_mfma_f32_16x16x32_bf16 v[144:147], v[176:179], v[196:199], v[144:147]
	v_mfma_f32_16x16x32_bf16 v[128:131], v[180:183], v[196:199], v[128:131]
	v_mfma_f32_16x16x32_bf16 v[100:103], v[188:191], v[196:199], v[100:103]
	v_mfma_f32_16x16x32_bf16 v[52:55], v[192:195], v[196:199], v[52:55]
	ds_read_b128 v[196:199], v152 offset:53760
	ds_write_b128 v229, v[204:207] offset:96
	global_load_dwordx4 v[200:203], v156, s[98:99]
	global_load_dwordx4 v[204:207], v156, s[98:99] offset:64
	s_waitcnt lgkmcnt(3)
	v_mfma_f32_16x16x32_bf16 v[140:143], v[176:179], v[184:187], v[140:143]
	v_mfma_f32_16x16x32_bf16 v[120:123], v[180:183], v[184:187], v[120:123]
	v_mfma_f32_16x16x32_bf16 v[88:91], v[188:191], v[184:187], v[88:91]
	v_mfma_f32_16x16x32_bf16 v[44:47], v[192:195], v[184:187], v[44:47]
	ds_read_b128 v[184:187], v152 offset:55296
	ds_write_b128 v230, v[208:211] offset:12288
	global_load_dwordx4 v[208:211], v158, s[100:101] offset:2048
	s_waitcnt lgkmcnt(3)
; DI f32x4 mfma16(bf16x8 a, bf16x8 b, f32x4 c) { return __builtin_amdgcn_mfma_f32_16x16x32_bf16(a, b, c, 0, 0, 0); }
; template <int NI, class XL, class EP>
; DI void gemm_tile(const u16* __restrict__ W, int ldw, int f0, int t0, int K, XL xl, EP ep, unsigned char* smem) {
;     ...
;   for (int it = 0; it < nk; ++it) {
;     const u16* Ws = S0 + (it & 1) * BUF; const u16* Xs = Ws + 128 * LST;
;     __builtin_amdgcn_s_setprio(1);
;     bf16x8 a[4];
; #pragma unroll
;     for (int mi = 0; mi < 4; ++mi) a[mi] = *(const bf16x8*)(Ws + (wf * 64 + mi * 16 + lr) * LST + lq * 8);
; #pragma unroll
;     for (int ni = 0; ni < NI; ++ni) {
;       const bf16x8 b = *(const bf16x8*)(Xs + (wt * (NI * 16) + ni * 16 + lr) * LST + lq * 8);
; #pragma unroll
;       for (int mi = 0; mi < 4; ++mi) acc[mi][ni] = mfma16(a[mi], b, acc[mi][ni]);
;     }
;     __builtin_amdgcn_sched_group_barrier(0x100, 6, 0);
; #pragma unroll
;     for (int ni = 0; ni < NI; ++ni) { __builtin_amdgcn_sched_group_barrier(0x008, 4, 0); if (ni + 2 < NI) __builtin_amdgcn_sched_group_barrier(0x100, 1, 0); }
;     __builtin_amdgcn_s_setprio(0);
;     if (it + 1 < nk) lstore((it + 1) & 1);
;     if (it + 2 < nk) gload(it + 2);
;     __syncthreads();
	v_mfma_f32_16x16x32_bf16 v[132:135], v[176:179], v[196:199], v[132:135]
	v_mfma_f32_16x16x32_bf16 v[108:111], v[180:183], v[196:199], v[108:111]
	v_mfma_f32_16x16x32_bf16 v[76:79], v[188:191], v[196:199], v[76:79]
	v_mfma_f32_16x16x32_bf16 v[40:43], v[192:195], v[196:199], v[40:43]
	ds_read_b128 v[196:199], v152 offset:56832
	ds_write_b128 v230, v[212:215] offset:12384
	global_load_dwordx4 v[212:215], v158, s[100:101] offset:2112
	s_waitcnt lgkmcnt(3)
	v_mfma_f32_16x16x32_bf16 v[124:127], v[176:179], v[184:187], v[124:127]
	v_mfma_f32_16x16x32_bf16 v[96:99], v[180:183], v[184:187], v[96:99]
	v_mfma_f32_16x16x32_bf16 v[68:71], v[188:191], v[184:187], v[68:71]
	v_mfma_f32_16x16x32_bf16 v[12:15], v[192:195], v[184:187], v[12:15]
	ds_read_b128 v[184:187], v152 offset:58368
	ds_write_b128 v230, v[220:223] offset:12480
	global_load_dwordx4 v[220:223], v158, s[100:101] offset:2176
	s_waitcnt lgkmcnt(3)
	v_mfma_f32_16x16x32_bf16 v[116:119], v[176:179], v[196:199], v[116:119]
	v_mfma_f32_16x16x32_bf16 v[84:87], v[180:183], v[196:199], v[84:87]
	v_mfma_f32_16x16x32_bf16 v[60:63], v[188:191], v[196:199], v[60:63]
	v_mfma_f32_16x16x32_bf16 v[8:11], v[192:195], v[196:199], v[8:11]
	ds_read_b128 v[196:199], v152 offset:59904
	ds_write_b128 v230, v[224:227] offset:12576
	global_load_dwordx4 v[224:227], v158, s[100:101] offset:2240
	s_waitcnt lgkmcnt(3)
	v_mfma_f32_16x16x32_bf16 v[104:107], v[176:179], v[184:187], v[104:107]
	v_mfma_f32_16x16x32_bf16 v[72:75], v[180:183], v[184:187], v[72:75]
	v_mfma_f32_16x16x32_bf16 v[56:59], v[188:191], v[184:187], v[56:59]
	v_mfma_f32_16x16x32_bf16 v[4:7], v[192:195], v[184:187], v[4:7]
	s_add_u32 s98, s98, s28
	s_addc_u32 s99, s99, s29
	s_add_u32 s100, s100, s26
	s_addc_u32 s101, s101, s27
	s_add_i32 s4, s4, 2
	s_waitcnt lgkmcnt(1)
	v_mfma_f32_16x16x32_bf16 v[92:95], v[176:179], v[196:199], v[92:95]
	v_mfma_f32_16x16x32_bf16 v[64:67], v[180:183], v[196:199], v[64:67]
	v_mfma_f32_16x16x32_bf16 v[48:51], v[188:191], v[196:199], v[48:51]
	v_mfma_f32_16x16x32_bf16 v[0:3], v[192:195], v[196:199], v[0:3]
	s_setprio 0
	s_cmp_eq_u32 s4, 29
	s_waitcnt lgkmcnt(0)
	s_barrier
	s_cbranch_scc0 .LBB0_945
	s_setprio 1
	ds_read_b128 v[176:179], v228 offset:0
	ds_read_b128 v[180:183], v228 offset:1536
	ds_read_b128 v[188:191], v228 offset:3072
	ds_read_b128 v[192:195], v228 offset:4608
	ds_read_b128 v[184:187], v152 offset:12288
	ds_read_b128 v[196:199], v152 offset:13824
	s_waitcnt lgkmcnt(1)
	v_mfma_f32_16x16x32_bf16 v[148:151], v[176:179], v[184:187], v[148:151]
	v_mfma_f32_16x16x32_bf16 v[136:139], v[180:183], v[184:187], v[136:139]
	v_mfma_f32_16x16x32_bf16 v[112:115], v[188:191], v[184:187], v[112:115]
	v_mfma_f32_16x16x32_bf16 v[80:83], v[192:195], v[184:187], v[80:83]
	ds_read_b128 v[184:187], v152 offset:15360
	s_waitcnt vmcnt(6)
	ds_write_b128 v229, v[20:23] offset:36864
	s_waitcnt lgkmcnt(2)
	v_mfma_f32_16x16x32_bf16 v[144:147], v[176:179], v[196:199], v[144:147]
	v_mfma_f32_16x16x32_bf16 v[128:131], v[180:183], v[196:199], v[128:131]
	v_mfma_f32_16x16x32_bf16 v[100:103], v[188:191], v[196:199], v[100:103]
	v_mfma_f32_16x16x32_bf16 v[52:55], v[192:195], v[196:199], v[52:55]
	ds_read_b128 v[196:199], v152 offset:16896
	ds_write_b128 v229, v[16:19] offset:36960
	global_load_dwordx4 v[20:23], v156, s[98:99]
	global_load_dwordx4 v[16:19], v156, s[98:99] offset:64
	s_waitcnt lgkmcnt(3)
	v_mfma_f32_16x16x32_bf16 v[140:143], v[176:179], v[184:187], v[140:143]
	v_mfma_f32_16x16x32_bf16 v[120:123], v[180:183], v[184:187], v[120:123]
	v_mfma_f32_16x16x32_bf16 v[88:91], v[188:191], v[184:187], v[88:91]
	v_mfma_f32_16x16x32_bf16 v[44:47], v[192:195], v[184:187], v[44:47]
	ds_read_b128 v[184:187], v152 offset:18432
	ds_write_b128 v230, v[36:39] offset:49152
	global_load_dwordx4 v[36:39], v158, s[100:101] offset:2048
	s_waitcnt lgkmcnt(3)
	v_mfma_f32_16x16x32_bf16 v[132:135], v[176:179], v[196:199], v[132:135]
	v_mfma_f32_16x16x32_bf16 v[108:111], v[180:183], v[196:199], v[108:111]
	v_mfma_f32_16x16x32_bf16 v[76:79], v[188:191], v[196:199], v[76:79]
	v_mfma_f32_16x16x32_bf16 v[40:43], v[192:195], v[196:199], v[40:43]
	ds_read_b128 v[196:199], v152 offset:19968
	ds_write_b128 v230, v[32:35] offset:49248
	global_load_dwordx4 v[32:35], v158, s[100:101] offset:2112
	s_waitcnt lgkmcnt(3)
	v_mfma_f32_16x16x32_bf16 v[124:127], v[176:179], v[184:187], v[124:127]
	v_mfma_f32_16x16x32_bf16 v[96:99], v[180:183], v[184:187], v[96:99]
	v_mfma_f32_16x16x32_bf16 v[68:71], v[188:191], v[184:187], v[68:71]
	v_mfma_f32_16x16x32_bf16 v[12:15], v[192:195], v[184:187], v[12:15]
	ds_read_b128 v[184:187], v152 offset:21504
	ds_write_b128 v230, v[28:31] offset:49344
	global_load_dwordx4 v[28:31], v158, s[100:101] offset:2176
	s_waitcnt lgkmcnt(3)
	v_mfma_f32_16x16x32_bf16 v[116:119], v[176:179], v[196:199], v[116:119]
	v_mfma_f32_16x16x32_bf16 v[84:87], v[180:183], v[196:199], v[84:87]
	v_mfma_f32_16x16x32_bf16 v[60:63], v[188:191], v[196:199], v[60:63]
	v_mfma_f32_16x16x32_bf16 v[8:11], v[192:195], v[196:199], v[8:11]
	ds_read_b128 v[196:199], v152 offset:23040
	ds_write_b128 v230, v[24:27] offset:49440
	global_load_dwordx4 v[24:27], v158, s[100:101] offset:2240
	s_waitcnt lgkmcnt(3)
	v_mfma_f32_16x16x32_bf16 v[104:107], v[176:179], v[184:187], v[104:107]
	v_mfma_f32_16x16x32_bf16 v[72:75], v[180:183], v[184:187], v[72:75]
	v_mfma_f32_16x16x32_bf16 v[56:59], v[188:191], v[184:187], v[56:59]
	v_mfma_f32_16x16x32_bf16 v[4:7], v[192:195], v[184:187], v[4:7]
	s_add_u32 s98, s98, s28
	s_addc_u32 s99, s99, s29
	s_add_u32 s100, s100, s26
	s_addc_u32 s101, s101, s27
	s_waitcnt lgkmcnt(1)
	v_mfma_f32_16x16x32_bf16 v[92:95], v[176:179], v[196:199], v[92:95]
	v_mfma_f32_16x16x32_bf16 v[64:67], v[180:183], v[196:199], v[64:67]
	v_mfma_f32_16x16x32_bf16 v[48:51], v[188:191], v[196:199], v[48:51]
	v_mfma_f32_16x16x32_bf16 v[0:3], v[192:195], v[196:199], v[0:3]
	s_setprio 0
	s_waitcnt lgkmcnt(0)
	s_barrier
; DI f32x4 mfma16(bf16x8 a, bf16x8 b, f32x4 c) { return __builtin_amdgcn_mfma_f32_16x16x32_bf16(a, b, c, 0, 0, 0); }
; template <int NI, class XL, class EP>
; DI void gemm_tile(const u16* __restrict__ W, int ldw, int f0, int t0, int K, XL xl, EP ep, unsigned char* smem) {
;     ...
;   for (int it = 0; it < nk; ++it) {
;     const u16* Ws = S0 + (it & 1) * BUF; const u16* Xs = Ws + 128 * LST;
;     __builtin_amdgcn_s_setprio(1);
;     bf16x8 a[4];
; #pragma unroll
;     for (int mi = 0; mi < 4; ++mi) a[mi] = *(const bf16x8*)(Ws + (wf * 64 + mi * 16 + lr) * LST + lq * 8);
; #pragma unroll
;     for (int ni = 0; ni < NI; ++ni) {
;       const bf16x8 b = *(const bf16x8*)(Xs + (wt * (NI * 16) + ni * 16 + lr) * LST + lq * 8);
; #pragma unroll
;       for (int mi = 0; mi < 4; ++mi) acc[mi][ni] = mfma16(a[mi], b, acc[mi][ni]);
;     }
;     __builtin_amdgcn_sched_group_barrier(0x100, 6, 0);
; #pragma unroll
;     for (int ni = 0; ni < NI; ++ni) { __builtin_amdgcn_sched_group_barrier(0x008, 4, 0); if (ni + 2 < NI) __builtin_amdgcn_sched_group_barrier(0x100, 1, 0); }
;     __builtin_amdgcn_s_setprio(0);
;     if (it + 1 < nk) lstore((it + 1) & 1);
;     if (it + 2 < nk) gload(it + 2);
;     __syncthreads();
	s_setprio 1
	ds_read_b128 v[176:179], v228 offset:36864
	ds_read_b128 v[180:183], v228 offset:38400
	ds_read_b128 v[188:191], v228 offset:39936
	ds_read_b128 v[192:195], v228 offset:41472
	ds_read_b128 v[184:187], v152 offset:49152
	ds_read_b128 v[196:199], v152 offset:50688
	s_waitcnt lgkmcnt(1)
	v_mfma_f32_16x16x32_bf16 v[148:151], v[176:179], v[184:187], v[148:151]
	v_mfma_f32_16x16x32_bf16 v[136:139], v[180:183], v[184:187], v[136:139]
	v_mfma_f32_16x16x32_bf16 v[112:115], v[188:191], v[184:187], v[112:115]
	v_mfma_f32_16x16x32_bf16 v[80:83], v[192:195], v[184:187], v[80:83]
	ds_read_b128 v[184:187], v152 offset:52224
	s_waitcnt vmcnt(6)
	ds_write_b128 v229, v[200:203] offset:0
	s_waitcnt lgkmcnt(2)
	v_mfma_f32_16x16x32_bf16 v[144:147], v[176:179], v[196:199], v[144:147]
	v_mfma_f32_16x16x32_bf16 v[128:131], v[180:183], v[196:199], v[128:131]
	v_mfma_f32_16x16x32_bf16 v[100:103], v[188:191], v[196:199], v[100:103]
	v_mfma_f32_16x16x32_bf16 v[52:55], v[192:195], v[196:199], v[52:55]
	ds_read_b128 v[196:199], v152 offset:53760
	ds_write_b128 v229, v[204:207] offset:96
	s_waitcnt lgkmcnt(3)
	v_mfma_f32_16x16x32_bf16 v[140:143], v[176:179], v[184:187], v[140:143]
	v_mfma_f32_16x16x32_bf16 v[120:123], v[180:183], v[184:187], v[120:123]
	v_mfma_f32_16x16x32_bf16 v[88:91], v[188:191], v[184:187], v[88:91]
	v_mfma_f32_16x16x32_bf16 v[44:47], v[192:195], v[184:187], v[44:47]
	ds_read_b128 v[184:187], v152 offset:55296
	ds_write_b128 v230, v[208:211] offset:12288
	s_waitcnt lgkmcnt(3)
	v_mfma_f32_16x16x32_bf16 v[132:135], v[176:179], v[196:199], v[132:135]
	v_mfma_f32_16x16x32_bf16 v[108:111], v[180:183], v[196:199], v[108:111]
	v_mfma_f32_16x16x32_bf16 v[76:79], v[188:191], v[196:199], v[76:79]
	v_mfma_f32_16x16x32_bf16 v[40:43], v[192:195], v[196:199], v[40:43]
	ds_read_b128 v[196:199], v152 offset:56832
	ds_write_b128 v230, v[212:215] offset:12384
	s_waitcnt lgkmcnt(3)
	v_mfma_f32_16x16x32_bf16 v[124:127], v[176:179], v[184:187], v[124:127]
	v_mfma_f32_16x16x32_bf16 v[96:99], v[180:183], v[184:187], v[96:99]
	v_mfma_f32_16x16x32_bf16 v[68:71], v[188:191], v[184:187], v[68:71]
	v_mfma_f32_16x16x32_bf16 v[12:15], v[192:195], v[184:187], v[12:15]
	ds_read_b128 v[184:187], v152 offset:58368
	ds_write_b128 v230, v[220:223] offset:12480
	s_waitcnt lgkmcnt(3)
	v_mfma_f32_16x16x32_bf16 v[116:119], v[176:179], v[196:199], v[116:119]
	v_mfma_f32_16x16x32_bf16 v[84:87], v[180:183], v[196:199], v[84:87]
	v_mfma_f32_16x16x32_bf16 v[60:63], v[188:191], v[196:199], v[60:63]
	v_mfma_f32_16x16x32_bf16 v[8:11], v[192:195], v[196:199], v[8:11]
	ds_read_b128 v[196:199], v152 offset:59904
	ds_write_b128 v230, v[224:227] offset:12576
	s_waitcnt lgkmcnt(3)
	v_mfma_f32_16x16x32_bf16 v[104:107], v[176:179], v[184:187], v[104:107]
	v_mfma_f32_16x16x32_bf16 v[72:75], v[180:183], v[184:187], v[72:75]
	v_mfma_f32_16x16x32_bf16 v[56:59], v[188:191], v[184:187], v[56:59]
	v_mfma_f32_16x16x32_bf16 v[4:7], v[192:195], v[184:187], v[4:7]
	s_add_i32 s4, s4, 2
	s_waitcnt lgkmcnt(1)
	v_mfma_f32_16x16x32_bf16 v[92:95], v[176:179], v[196:199], v[92:95]
	v_mfma_f32_16x16x32_bf16 v[64:67], v[180:183], v[196:199], v[64:67]
	v_mfma_f32_16x16x32_bf16 v[48:51], v[188:191], v[196:199], v[48:51]
	v_mfma_f32_16x16x32_bf16 v[0:3], v[192:195], v[196:199], v[0:3]
	s_setprio 0
	s_waitcnt lgkmcnt(0)
	s_barrier
	s_setprio 1
	v_lshl_add_u32 v152, v175, 1, v172
	ds_read_b128 v[156:159], v152
	v_lshl_add_u32 v171, v173, 1, v172
	ds_read_b128 v[172:175], v152 offset:1536
	ds_read_b128 v[180:183], v152 offset:3072
	ds_read_b128 v[184:187], v152 offset:4608
	ds_read_b128 v[176:179], v171 offset:12288
	ds_read_b128 v[188:191], v171 offset:13824
	s_waitcnt lgkmcnt(1)
	v_mfma_f32_16x16x32_bf16 v[148:151], v[156:159], v[176:179], v[148:151]
	v_mfma_f32_16x16x32_bf16 v[136:139], v[172:175], v[176:179], v[136:139]
	v_mfma_f32_16x16x32_bf16 v[112:115], v[180:183], v[176:179], v[112:115]
	v_mfma_f32_16x16x32_bf16 v[80:83], v[184:187], v[176:179], v[80:83]
	ds_read_b128 v[176:179], v171 offset:15360
	s_waitcnt lgkmcnt(1)
	v_mfma_f32_16x16x32_bf16 v[144:147], v[156:159], v[188:191], v[144:147]
	v_mfma_f32_16x16x32_bf16 v[128:131], v[172:175], v[188:191], v[128:131]
	v_mfma_f32_16x16x32_bf16 v[100:103], v[180:183], v[188:191], v[100:103]
	v_mfma_f32_16x16x32_bf16 v[188:191], v[184:187], v[188:191], v[52:55]
	s_nop 2
	ds_read_b128 v[52:55], v171 offset:16896
	s_waitcnt lgkmcnt(1)
	v_mfma_f32_16x16x32_bf16 v[192:195], v[156:159], v[176:179], v[140:143]
	v_mfma_f32_16x16x32_bf16 v[120:123], v[172:175], v[176:179], v[120:123]
	v_mfma_f32_16x16x32_bf16 v[88:91], v[180:183], v[176:179], v[88:91]
	v_mfma_f32_16x16x32_bf16 v[176:179], v[184:187], v[176:179], v[44:47]
	s_nop 2
	ds_read_b128 v[44:47], v171 offset:18432
	s_waitcnt lgkmcnt(1)
	v_mfma_f32_16x16x32_bf16 v[196:199], v[156:159], v[52:55], v[132:135]
	v_mfma_f32_16x16x32_bf16 v[108:111], v[172:175], v[52:55], v[108:111]
	v_mfma_f32_16x16x32_bf16 v[76:79], v[180:183], v[52:55], v[76:79]
	v_mfma_f32_16x16x32_bf16 v[200:203], v[184:187], v[52:55], v[40:43]
	s_nop 2
	ds_read_b128 v[40:43], v171 offset:19968
	s_waitcnt lgkmcnt(1)
	v_mfma_f32_16x16x32_bf16 v[204:207], v[156:159], v[44:47], v[124:127]
	v_mfma_f32_16x16x32_bf16 v[96:99], v[172:175], v[44:47], v[96:99]
	v_mfma_f32_16x16x32_bf16 v[68:71], v[180:183], v[44:47], v[68:71]
	v_mfma_f32_16x16x32_bf16 v[12:15], v[184:187], v[44:47], v[12:15]
	ds_read_b128 v[44:47], v171 offset:21504
	s_waitcnt lgkmcnt(1)
	v_mfma_f32_16x16x32_bf16 v[208:211], v[156:159], v[40:43], v[116:119]
	v_mfma_f32_16x16x32_bf16 v[84:87], v[172:175], v[40:43], v[84:87]
	v_mfma_f32_16x16x32_bf16 v[212:215], v[180:183], v[40:43], v[60:63]
	v_mfma_f32_16x16x32_bf16 v[8:11], v[184:187], v[40:43], v[8:11]
	ds_read_b128 v[40:43], v171 offset:23040
	s_waitcnt lgkmcnt(1)
	v_mfma_f32_16x16x32_bf16 v[220:223], v[156:159], v[44:47], v[104:107]
	v_mfma_f32_16x16x32_bf16 v[72:75], v[172:175], v[44:47], v[72:75]
	v_mfma_f32_16x16x32_bf16 v[224:227], v[180:183], v[44:47], v[56:59]
	v_mfma_f32_16x16x32_bf16 v[4:7], v[184:187], v[44:47], v[4:7]
	s_waitcnt lgkmcnt(0)
	v_mfma_f32_16x16x32_bf16 v[156:159], v[156:159], v[40:43], v[92:95]
	v_mfma_f32_16x16x32_bf16 v[172:175], v[172:175], v[40:43], v[64:67]
	v_mfma_f32_16x16x32_bf16 v[180:183], v[180:183], v[40:43], v[48:51]
	v_mfma_f32_16x16x32_bf16 v[184:187], v[184:187], v[40:43], v[0:3]
	s_setprio 0
	s_waitcnt vmcnt(5)
	ds_write_b128 v170, v[20:23] offset:36864
	s_waitcnt vmcnt(4)
	ds_write_b128 v170, v[16:19] offset:36960
	s_waitcnt vmcnt(3)
	ds_write_b128 v169, v[36:39] offset:49152
	s_waitcnt vmcnt(2)
	ds_write_b128 v169, v[32:35] offset:49248
	s_waitcnt vmcnt(1)
	ds_write_b128 v169, v[28:31] offset:49344
	s_waitcnt vmcnt(0)
	ds_write_b128 v169, v[24:27] offset:49440
	s_waitcnt lgkmcnt(0)
	s_barrier
; DI float sigmoidf_(float x) { return 1.0f / (1.0f + __expf(-x)); }
; DI void store4(u16* dst, f32x4 v) { uint2 w; w.x = cvtpk(v[0], v[1]); w.y = cvtpk(v[2], v[3]); *(uint2*)dst = w; }
; template <int NI, class XL, class EP>
; DI void gemm_tile(const u16* __restrict__ W, int ldw, int f0, int t0, int K, XL xl, EP ep, unsigned char* smem) {
;     ...
;     for (int ni = 0; ni < NI; ++ni) {
;       const bf16x8 b = *(const bf16x8*)(Xs + (wt * (NI * 16) + ni * 16 + lr) * LST + lq * 8);
; #pragma unroll
;       for (int mi = 0; mi < 4; ++mi) acc[mi][ni] = mfma16(a[mi], b, acc[mi][ni]);
;     }
;     __builtin_amdgcn_sched_group_barrier(0x100, 6, 0);
; #pragma unroll
;     for (int ni = 0; ni < NI; ++ni) { __builtin_amdgcn_sched_group_barrier(0x008, 4, 0); if (ni + 2 < NI) __builtin_amdgcn_sched_group_barrier(0x100, 1, 0); }
;     __builtin_amdgcn_s_setprio(0);
; DI void phase8(const Params& p, const Sched& sched, unsigned char* smem) {
;     ...
; #pragma unroll
;       for (int h2 = 0; h2 < 2; ++h2) {
;         const int fl = wf * 16 + lq * 4, fc = (2 * wf + h2) * 16 + lq * 4, F = tn * 64 + fc;
;         __syncthreads();
; #pragma unroll
;         for (int ni = 0; ni < 8; ++ni) *(f32x4*)(gl + (wt * 128 + ni * 16 + lr) * 36 + fl) = acc[2 * h2][ni];
;         __syncthreads();
;         const float4 w0 = *(const float4*)(p.conv_w + F), w1 = *(const float4*)(p.conv_w + FF + F), w2 = *(const float4*)(p.conv_w + 2 * FF + F), cb = *(const float4*)(p.conv_b + F);
; #pragma unroll
;         for (int ni = 0; ni < 8; ++ni) {
;           const int row = wt * 128 + ni * 16 + lr;
;           const f32x4 gv = acc[2 * h2][ni], uv = acc[2 * h2 + 1][ni];
;           if (row >= 2) {
;             const f32x4 g1 = *(const f32x4*)(gl + (row - 1) * 36 + fl), g2 = *(const f32x4*)(gl + (row - 2) * 36 + fl);
;             f32x4 o;
;             o[0] = cb.x + w0.x * g2[0] + w1.x * g1[0] + w2.x * gv[0];
;             o[1] = cb.y + w0.y * g2[1] + w1.y * g1[1] + w2.y * gv[1];
;             o[2] = cb.z + w0.z * g2[2] + w1.z * g1[2] + w2.z * gv[2];
;             o[3] = cb.w + w0.w * g2[3] + w1.w * g1[3] + w2.w * gv[3];
; #pragma unroll
;             for (int j = 0; j < 4; ++j) o[j] = o[j] * sigmoidf_(o[j]) * uv[j];
;             store4(Ls + row * 72 + fc, o);
;           } else {
;             *(f32x4*)(gside + ((size_t)tm * 4 + row) * FF + F) = gv;
	s_setprio 1
	ds_read_b128 v[0:3], v152 offset:36864
	ds_read_b128 v[228:231], v152 offset:38400
	ds_read_b128 v[232:235], v152 offset:39936
	ds_read_b128 v[236:239], v152 offset:41472
	ds_read_b128 v[16:19], v171 offset:49152
	ds_read_b128 v[20:23], v171 offset:50688
	s_waitcnt lgkmcnt(1)
	v_mfma_f32_16x16x32_bf16 v[140:143], v[0:3], v[16:19], v[148:151]
	v_mfma_f32_16x16x32_bf16 v[136:139], v[228:231], v[16:19], v[136:139]
	v_mfma_f32_16x16x32_bf16 v[60:63], v[232:235], v[16:19], v[112:115]
	v_mfma_f32_16x16x32_bf16 v[56:59], v[236:239], v[16:19], v[80:83]
	ds_read_b128 v[16:19], v171 offset:52224
	s_waitcnt lgkmcnt(1)
	v_mfma_f32_16x16x32_bf16 v[132:135], v[0:3], v[20:23], v[144:147]
	v_mfma_f32_16x16x32_bf16 v[128:131], v[228:231], v[20:23], v[128:131]
	v_mfma_f32_16x16x32_bf16 v[52:55], v[232:235], v[20:23], v[100:103]
	v_mfma_f32_16x16x32_bf16 v[48:51], v[236:239], v[20:23], v[188:191]
	ds_read_b128 v[20:23], v171 offset:53760
	s_waitcnt lgkmcnt(1)
	v_mfma_f32_16x16x32_bf16 v[124:127], v[0:3], v[16:19], v[192:195]
	v_mfma_f32_16x16x32_bf16 v[120:123], v[228:231], v[16:19], v[120:123]
	v_mfma_f32_16x16x32_bf16 v[44:47], v[232:235], v[16:19], v[88:91]
	v_mfma_f32_16x16x32_bf16 v[40:43], v[236:239], v[16:19], v[176:179]
	ds_read_b128 v[16:19], v171 offset:55296
	s_waitcnt lgkmcnt(1)
	v_mfma_f32_16x16x32_bf16 v[116:119], v[0:3], v[20:23], v[196:199]
	v_mfma_f32_16x16x32_bf16 v[112:115], v[228:231], v[20:23], v[108:111]
	v_mfma_f32_16x16x32_bf16 v[36:39], v[232:235], v[20:23], v[76:79]
	v_mfma_f32_16x16x32_bf16 v[32:35], v[236:239], v[20:23], v[200:203]
	ds_read_b128 v[64:67], v171 offset:56832
	s_waitcnt lgkmcnt(1)
	v_mfma_f32_16x16x32_bf16 v[108:111], v[0:3], v[16:19], v[204:207]
	v_mfma_f32_16x16x32_bf16 v[104:107], v[228:231], v[16:19], v[96:99]
	v_mfma_f32_16x16x32_bf16 v[28:31], v[232:235], v[16:19], v[68:71]
	v_mfma_f32_16x16x32_bf16 v[24:27], v[236:239], v[16:19], v[12:15]
	s_nop 1
	ds_read_b128 v[68:71], v171 offset:58368
	s_waitcnt lgkmcnt(1)
	v_mfma_f32_16x16x32_bf16 v[100:103], v[0:3], v[64:67], v[208:211]
	v_mfma_f32_16x16x32_bf16 v[96:99], v[228:231], v[64:67], v[84:87]
	v_mfma_f32_16x16x32_bf16 v[20:23], v[232:235], v[64:67], v[212:215]
	v_mfma_f32_16x16x32_bf16 v[16:19], v[236:239], v[64:67], v[8:11]
	ds_read_b128 v[76:79], v171 offset:59904
	s_waitcnt lgkmcnt(1)
	v_mfma_f32_16x16x32_bf16 v[92:95], v[0:3], v[68:71], v[220:223]
	v_mfma_f32_16x16x32_bf16 v[72:75], v[228:231], v[68:71], v[72:75]
	v_mfma_f32_16x16x32_bf16 v[12:15], v[232:235], v[68:71], v[224:227]
	v_mfma_f32_16x16x32_bf16 v[8:11], v[236:239], v[68:71], v[4:7]
	s_waitcnt lgkmcnt(0)
	v_mfma_f32_16x16x32_bf16 v[64:67], v[0:3], v[76:79], v[156:159]
	v_mfma_f32_16x16x32_bf16 v[68:71], v[228:231], v[76:79], v[172:175]
	v_mfma_f32_16x16x32_bf16 v[0:3], v[232:235], v[76:79], v[180:183]
	v_mfma_f32_16x16x32_bf16 v[4:7], v[236:239], v[76:79], v[184:187]
	s_setprio 0
	v_lshlrev_b32_e32 v76, 2, v168
	v_lshl_or_b32 v152, v155, 4, v76
	v_lshl_or_b32 v156, v155, 5, v76
	v_lshlrev_b32_e32 v76, 2, v152
	v_mad_u32_u24 v77, v154, s47, v160
	v_add_u32_e32 v159, v77, v76
	v_mad_u32_u24 v77, v154, s47, v161
	v_add_u32_e32 v168, v77, v76
	v_mad_u32_u24 v77, v154, s47, v162
	s_lshl_b32 s57, s56, 6
	v_add_u32_e32 v169, v77, v76
	v_mad_u32_u24 v77, v154, s47, v163
	v_add_u32_e32 v170, v77, v76
	v_mad_u32_u24 v77, v154, s47, v164
	v_add_u32_e32 v144, s57, v156
	v_add_u32_e32 v171, v77, v76
	v_mad_u32_u24 v77, v154, s47, v165
	v_ashrrev_i32_e32 v145, 31, v144
	v_add_u32_e32 v172, v77, v76
	v_mad_u32_u24 v77, v154, s47, v166
	v_lshlrev_b64 v[146:147], 2, v[144:145]
	v_mad_u32_u24 v158, v154, s47, v76
	v_add_u32_e32 v173, v77, v76
	v_lshl_add_u64 v[148:149], s[68:69], 0, v[146:147]
	v_lshl_add_u64 v[76:77], s[22:23], 0, v[146:147]
	v_lshl_add_u64 v[78:79], s[24:25], 0, v[146:147]
	v_lshl_add_u64 v[150:151], s[70:71], 0, v[146:147]
	global_load_dwordx4 v[84:87], v[148:149], off
	global_load_dwordx4 v[80:83], v[76:77], off
	global_load_dwordx4 v[88:91], v[150:151], off
	global_load_dwordx4 v[76:79], v[78:79], off
	s_barrier
	s_barrier
	ds_write_b128 v158, v[140:143]
	ds_write_b128 v159, v[132:135]
	ds_write_b128 v168, v[124:127]
	ds_write_b128 v169, v[116:119]
	ds_write_b128 v170, v[108:111]
	ds_write_b128 v171, v[100:103]
	ds_write_b128 v172, v[92:95]
	ds_write_b128 v173, v[64:67]
	s_waitcnt lgkmcnt(0)
	s_barrier
	v_cmp_gt_u32_e64 s[4:5], 2, v154
	v_lshl_or_b32 v157, s30, 1, v154
	s_and_saveexec_b64 s[6:7], s[4:5]
	s_xor_b64 s[6:7], exec, s[6:7]
	s_cbranch_execz .LBB0_948
	s_ashr_i32 s31, s30, 31
	s_lshl_b64 s[34:35], s[30:31], 2
	v_or_b32_e32 v155, s34, v154
	v_mov_b64_e32 v[174:175], s[16:17]
	v_mad_u64_u32 v[174:175], s[58:59], v155, s48, v[174:175]
	v_mad_i32_i24 v175, s35, v167, v175
	v_lshl_add_u64 v[174:175], v[174:175], 0, v[146:147]
	global_store_dwordx4 v[174:175], v[140:143], off
	s_nop 1
	v_mov_b64_e32 v[140:141], s[10:11]
	v_mad_u64_u32 v[140:141], s[34:35], v157, s48, v[140:141]
	v_mad_i32_i24 v141, s31, v167, v141
	v_lshl_add_u64 v[140:141], v[140:141], 0, v[146:147]
	global_store_dwordx4 v[140:141], v[136:139], off
